# v28 + non-temporal hint on the w_in and w_ff1 GEMM epilogue stores (large write-once outputs)
# baseline (speedup 1.0000x reference)
.LBB0_230:
	v_lshl_add_u64 v[96:97], v[192:193], 2, s[68:69]
	global_load_dword v169, v[96:97], off
	global_load_dwordx4 v[90:93], v[152:153], off
	global_load_dword v171, v[96:97], off offset:64
	global_load_dword v173, v[96:97], off offset:128
	global_load_dword v175, v[96:97], off offset:192
	global_load_dword v165, v[96:97], off offset:512
	global_load_dword v122, v[96:97], off offset:576
	global_load_dword v95, v[96:97], off offset:640
	global_load_dword v1, v[96:97], off offset:704
	s_cmp_lt_u32 s6, 36
	s_cselect_b64 vcc, -1, 0
	s_and_b64 s[4:5], vcc, exec
	s_movk_i32 s4, 0xffe8
	s_cselect_b32 s4, s4, 0xffffffdc
	s_add_i32 s4, s4, s6
	s_ashr_i32 s28, s4, 2
	s_lshl_b32 s5, s28, 1
	s_and_b64 s[34:35], vcc, exec
	s_cselect_b32 s4, s71, s57
	s_cselect_b32 s7, s70, s56
	s_ashr_i32 s29, s28, 31
	s_and_b32 s21, s30, 0x300
	s_lshl_b64 s[28:29], s[28:29], 25
	s_add_u32 s7, s7, s28
	s_addc_u32 s4, s4, s29
	s_lshl_b32 s21, s21, 1
	s_add_u32 s28, s7, s21
	s_addc_u32 s29, s4, 0
	s_sub_i32 s7, 12, s5
	v_and_b32_e32 v167, 0xfcf, v192
	s_waitcnt vmcnt(0)
	v_pk_mul_f32 v[200:201], v[70:71], v[178:179] op_sel_hi:[1,0]
	v_pk_mul_f32 v[202:203], v[66:67], v[178:179] op_sel_hi:[1,0]
	v_pk_mul_f32 v[204:205], v[72:73], v[178:179] op_sel_hi:[1,0]
	v_pk_mul_f32 v[206:207], v[68:69], v[178:179] op_sel_hi:[1,0]
	v_lshlrev_b32_e32 v179, s7, v192
	v_lshrrev_b32_e32 v177, s5, v167
	s_lshl_b32 s4, s31, 12
	v_and_b32_e32 v179, 0xfff, v179
	v_add_u32_e32 v123, 0x80, v192
	v_or3_b32 v192, v177, v179, s4
	v_pk_mul_f32 v[202:203], v[202:203], v[184:185]
	v_pk_mul_f32 v[206:207], v[206:207], v[186:187]
	v_pk_mul_f32 v[200:201], v[200:201], v[188:189]
	v_pk_mul_f32 v[204:205], v[204:205], v[190:191]
	v_cndmask_b32_e32 v94, 1.0, v199, vcc
	v_ashrrev_i32_e32 v193, 31, v192
	v_lshl_add_u64 v[96:97], s[28:29], 0, v[150:151]
	v_lshlrev_b64 v[192:193], 11, v[192:193]
	v_lshl_add_u64 v[192:193], v[96:97], 0, v[192:193]
	v_cvt_f32_i32_e32 v171, v171
	v_cvt_f32_i32_e32 v169, v169
	v_cvt_f32_i32_e32 v1, v1
	v_mul_f32_e32 v177, v90, v169
	v_mul_f32_e32 v179, v91, v169
	v_mul_f32_e32 v212, v92, v169
	v_mul_f32_e32 v169, v93, v169
	v_cvt_f64_f32_e32 v[208:209], v177
	v_cvt_f64_f32_e32 v[210:211], v179
	v_cvt_f64_f32_e32 v[212:213], v212
	v_cvt_f64_f32_e32 v[214:215], v169
	v_mul_f64 v[216:217], v[208:209], s[18:19]
	v_mul_f64 v[218:219], v[210:211], s[18:19]
	v_mul_f64 v[220:221], v[212:213], s[18:19]
	v_mul_f64 v[222:223], v[214:215], s[18:19]
	v_rndne_f64_e32 v[216:217], v[216:217]
	v_rndne_f64_e32 v[218:219], v[218:219]
	v_rndne_f64_e32 v[220:221], v[220:221]
	v_rndne_f64_e32 v[222:223], v[222:223]
	v_fma_f64 v[208:209], v[208:209], s[18:19], -v[216:217]
	v_fma_f64 v[210:211], v[210:211], s[18:19], -v[218:219]
	v_fma_f64 v[212:213], v[212:213], s[18:19], -v[220:221]
	v_fma_f64 v[214:215], v[214:215], s[18:19], -v[222:223]
	v_cvt_f32_f64_e32 v169, v[208:209]
	v_cvt_f32_f64_e32 v177, v[210:211]
	v_cvt_f32_f64_e32 v179, v[212:213]
	v_cvt_f32_f64_e32 v213, v[214:215]
	v_sin_f32_e32 v208, v169
	v_cos_f32_e32 v210, v169
	v_sin_f32_e32 v209, v177
	v_cos_f32_e32 v211, v177
	v_sin_f32_e32 v212, v179
	v_cos_f32_e32 v214, v179
	v_cos_f32_e32 v215, v213
	v_sin_f32_e32 v213, v213
	v_pk_mul_f32 v[216:217], v[202:203], v[210:211]
	v_pk_mul_f32 v[202:203], v[202:203], v[208:209]
	v_pk_mul_f32 v[218:219], v[206:207], v[214:215]
	v_pk_mul_f32 v[206:207], v[206:207], v[212:213]
	v_pk_fma_f32 v[216:217], v[200:201], v[208:209], v[216:217]
	v_pk_fma_f32 v[200:201], v[200:201], v[210:211], v[202:203] neg_lo:[0,0,1] neg_hi:[0,0,1]
	v_pk_fma_f32 v[202:203], v[204:205], v[212:213], v[218:219]
	v_pk_fma_f32 v[204:205], v[204:205], v[214:215], v[206:207] neg_lo:[0,0,1] neg_hi:[0,0,1]
	v_pk_mul_f32 v[200:201], v[94:95], v[200:201] op_sel_hi:[0,1]
	v_pk_mul_f32 v[202:203], v[94:95], v[202:203] op_sel_hi:[0,1]
	v_pk_mul_f32 v[204:205], v[94:95], v[204:205] op_sel_hi:[0,1]
	v_pk_mul_f32 v[206:207], v[94:95], v[216:217] op_sel_hi:[0,1]
	v_cvt_pk_bf16_f32 v200, v200, v201
	v_cvt_pk_bf16_f32 v201, v204, v205
	v_cvt_pk_bf16_f32 v205, v202, v203
	v_pk_mul_f32 v[202:203], v[46:47], v[178:179] op_sel_hi:[1,0]
	v_cvt_pk_bf16_f32 v204, v206, v207
	global_store_dwordx2 v[192:193], v[200:201], off nt
	global_store_dwordx2 v[192:193], v[204:205], off offset:128 nt
	v_pk_mul_f32 v[200:201], v[50:51], v[178:179] op_sel_hi:[1,0]
	v_pk_mul_f32 v[202:203], v[202:203], v[140:141]
	v_pk_mul_f32 v[200:201], v[200:201], v[144:145]
	v_pk_mul_f32 v[204:205], v[202:203], v[210:211]
	v_pk_mul_f32 v[202:203], v[202:203], v[208:209]
	v_pk_mul_f32 v[206:207], v[48:49], v[178:179] op_sel_hi:[1,0]
	v_pk_fma_f32 v[204:205], v[200:201], v[208:209], v[204:205]
	v_pk_fma_f32 v[200:201], v[200:201], v[210:211], v[202:203] neg_lo:[0,0,1] neg_hi:[0,0,1]
	v_pk_mul_f32 v[202:203], v[52:53], v[178:179] op_sel_hi:[1,0]
	v_pk_mul_f32 v[206:207], v[206:207], v[142:143]
	v_pk_mul_f32 v[202:203], v[202:203], v[180:181]
	v_pk_mul_f32 v[208:209], v[206:207], v[214:215]
	v_pk_mul_f32 v[206:207], v[206:207], v[212:213]
	v_pk_fma_f32 v[208:209], v[202:203], v[212:213], v[208:209]
	v_pk_fma_f32 v[202:203], v[202:203], v[214:215], v[206:207] neg_lo:[0,0,1] neg_hi:[0,0,1]
	v_pk_mul_f32 v[200:201], v[94:95], v[200:201] op_sel_hi:[0,1]
	v_pk_mul_f32 v[202:203], v[94:95], v[202:203] op_sel_hi:[0,1]
	v_pk_mul_f32 v[204:205], v[94:95], v[204:205] op_sel_hi:[0,1]
	v_pk_mul_f32 v[208:209], v[94:95], v[208:209] op_sel_hi:[0,1]
	v_cvt_pk_bf16_f32 v200, v200, v201
	v_cvt_pk_bf16_f32 v201, v202, v203
	v_mul_f32_e32 v179, v90, v171
	v_cvt_pk_bf16_f32 v202, v204, v205
	v_cvt_pk_bf16_f32 v203, v208, v209
	global_store_dwordx2 v[192:193], v[200:201], off offset:256 nt
	global_store_dwordx2 v[192:193], v[202:203], off offset:384 nt
	v_cvt_f64_f32_e32 v[192:193], v179
	v_mul_f64 v[200:201], v[192:193], s[18:19]
	v_rndne_f64_e32 v[200:201], v[200:201]
	v_fma_f64 v[192:193], v[192:193], s[18:19], -v[200:201]
	v_cvt_f32_f64_e32 v179, v[192:193]
	v_sin_f32_e32 v192, v179
	v_cos_f32_e32 v200, v179
	v_mul_f32_e32 v179, v91, v171
	v_cvt_f64_f32_e32 v[202:203], v179
	v_mul_f64 v[204:205], v[202:203], s[18:19]
	v_rndne_f64_e32 v[204:205], v[204:205]
	v_fma_f64 v[202:203], v[202:203], s[18:19], -v[204:205]
	v_cvt_f32_f64_e32 v179, v[202:203]
	v_sin_f32_e32 v193, v179
	v_cos_f32_e32 v201, v179
	v_mul_f32_e32 v179, v92, v171
	v_mul_f32_e32 v171, v93, v171
	v_cvt_f64_f32_e32 v[202:203], v179
	v_cvt_f64_f32_e32 v[206:207], v171
	v_mul_f64 v[204:205], v[202:203], s[18:19]
	v_mul_f64 v[208:209], v[206:207], s[18:19]
	v_or_b32_e32 v169, 16, v167
	v_rndne_f64_e32 v[204:205], v[204:205]
	v_rndne_f64_e32 v[208:209], v[208:209]
	v_lshlrev_b32_e32 v177, s7, v169
	v_fma_f64 v[202:203], v[202:203], s[18:19], -v[204:205]
	v_fma_f64 v[206:207], v[206:207], s[18:19], -v[208:209]
	v_and_b32_e32 v177, 0xfff, v177
	v_cvt_f32_f64_e32 v179, v[202:203]
	v_cvt_f32_f64_e32 v171, v[206:207]
	v_sin_f32_e32 v202, v179
	v_cos_f32_e32 v204, v179
	v_sin_f32_e32 v203, v171
	v_cos_f32_e32 v205, v171
	v_pk_mul_f32 v[210:211], v[66:67], v[176:177] op_sel_hi:[1,0]
	v_pk_mul_f32 v[208:209], v[70:71], v[176:177] op_sel_hi:[1,0]
	v_pk_mul_f32 v[210:211], v[210:211], v[134:135]
	v_pk_mul_f32 v[208:209], v[208:209], v[138:139]
	v_pk_mul_f32 v[212:213], v[210:211], v[200:201]
	v_pk_mul_f32 v[210:211], v[210:211], v[192:193]
	v_pk_mul_f32 v[214:215], v[68:69], v[176:177] op_sel_hi:[1,0]
	v_lshrrev_b32_e32 v169, s5, v169
	v_pk_fma_f32 v[212:213], v[208:209], v[192:193], v[212:213]
	v_pk_fma_f32 v[208:209], v[208:209], v[200:201], v[210:211] neg_lo:[0,0,1] neg_hi:[0,0,1]
	v_pk_mul_f32 v[210:211], v[72:73], v[176:177] op_sel_hi:[1,0]
	v_pk_mul_f32 v[214:215], v[214:215], v[132:133]
	v_or3_b32 v206, v169, v177, s4
	v_pk_mul_f32 v[210:211], v[210:211], v[136:137]
	v_pk_mul_f32 v[216:217], v[214:215], v[204:205]
	v_pk_mul_f32 v[214:215], v[214:215], v[202:203]
	v_ashrrev_i32_e32 v207, 31, v206
	v_pk_fma_f32 v[216:217], v[210:211], v[202:203], v[216:217]
	v_pk_fma_f32 v[210:211], v[210:211], v[204:205], v[214:215] neg_lo:[0,0,1] neg_hi:[0,0,1]
	v_lshlrev_b64 v[206:207], 11, v[206:207]
	v_pk_mul_f32 v[212:213], v[94:95], v[212:213] op_sel_hi:[0,1]
	v_pk_mul_f32 v[208:209], v[94:95], v[208:209] op_sel_hi:[0,1]
	v_pk_mul_f32 v[216:217], v[94:95], v[216:217] op_sel_hi:[0,1]
	v_pk_mul_f32 v[210:211], v[94:95], v[210:211] op_sel_hi:[0,1]
	v_lshl_add_u64 v[206:207], v[96:97], 0, v[206:207]
	v_cvt_pk_bf16_f32 v208, v208, v209
	v_cvt_pk_bf16_f32 v209, v210, v211
	v_cvt_pk_bf16_f32 v210, v212, v213
	v_cvt_pk_bf16_f32 v211, v216, v217
	global_store_dwordx2 v[206:207], v[208:209], off nt
	global_store_dwordx2 v[206:207], v[210:211], off offset:128 nt
	v_pk_mul_f32 v[210:211], v[46:47], v[176:177] op_sel_hi:[1,0]
	v_pk_mul_f32 v[208:209], v[50:51], v[176:177] op_sel_hi:[1,0]
	v_pk_mul_f32 v[210:211], v[210:211], v[124:125]
	v_pk_mul_f32 v[208:209], v[208:209], v[128:129]
	v_pk_mul_f32 v[212:213], v[210:211], v[200:201]
	v_cvt_f32_i32_e32 v171, v173
	v_pk_fma_f32 v[212:213], v[208:209], v[192:193], v[212:213]
	v_pk_mul_f32 v[192:193], v[210:211], v[192:193]
	v_pk_mul_f32 v[212:213], v[94:95], v[212:213] op_sel_hi:[0,1]
	v_pk_fma_f32 v[192:193], v[208:209], v[200:201], v[192:193] neg_lo:[0,0,1] neg_hi:[0,0,1]
	v_pk_mul_f32 v[208:209], v[48:49], v[176:177] op_sel_hi:[1,0]
	v_pk_mul_f32 v[200:201], v[52:53], v[176:177] op_sel_hi:[1,0]
	v_pk_mul_f32 v[208:209], v[208:209], v[126:127]
	v_pk_mul_f32 v[200:201], v[200:201], v[130:131]
	v_pk_mul_f32 v[210:211], v[208:209], v[204:205]
	v_pk_mul_f32 v[192:193], v[94:95], v[192:193] op_sel_hi:[0,1]
	v_pk_fma_f32 v[210:211], v[200:201], v[202:203], v[210:211]
	v_pk_mul_f32 v[202:203], v[208:209], v[202:203]
	v_pk_mul_f32 v[210:211], v[94:95], v[210:211] op_sel_hi:[0,1]
	v_pk_fma_f32 v[200:201], v[200:201], v[204:205], v[202:203] neg_lo:[0,0,1] neg_hi:[0,0,1]
	v_cvt_pk_bf16_f32 v192, v192, v193
	v_pk_mul_f32 v[200:201], v[94:95], v[200:201] op_sel_hi:[0,1]
	v_cvt_pk_bf16_f32 v193, v200, v201
	v_mul_f32_e32 v177, v90, v171
	v_cvt_pk_bf16_f32 v200, v212, v213
	v_cvt_pk_bf16_f32 v201, v210, v211
	global_store_dwordx2 v[206:207], v[192:193], off offset:256 nt
	global_store_dwordx2 v[206:207], v[200:201], off offset:384 nt
	v_cvt_f64_f32_e32 v[192:193], v177
	v_mul_f64 v[200:201], v[192:193], s[18:19]
	v_rndne_f64_e32 v[200:201], v[200:201]
	v_fma_f64 v[192:193], v[192:193], s[18:19], -v[200:201]
	v_cvt_f32_f64_e32 v177, v[192:193]
	v_sin_f32_e32 v192, v177
	v_cos_f32_e32 v200, v177
	v_mul_f32_e32 v177, v91, v171
	v_cvt_f64_f32_e32 v[202:203], v177
	v_mul_f64 v[204:205], v[202:203], s[18:19]
	v_rndne_f64_e32 v[204:205], v[204:205]
	v_fma_f64 v[202:203], v[202:203], s[18:19], -v[204:205]
	v_cvt_f32_f64_e32 v177, v[202:203]
	v_sin_f32_e32 v193, v177
	v_cos_f32_e32 v201, v177
	v_mul_f32_e32 v177, v92, v171
	v_mul_f32_e32 v171, v93, v171
	v_cvt_f64_f32_e32 v[202:203], v177
	v_cvt_f64_f32_e32 v[206:207], v171
	v_mul_f64 v[204:205], v[202:203], s[18:19]
	v_mul_f64 v[208:209], v[206:207], s[18:19]
	v_rndne_f64_e32 v[204:205], v[204:205]
	v_rndne_f64_e32 v[208:209], v[208:209]
	v_fma_f64 v[202:203], v[202:203], s[18:19], -v[204:205]
	v_fma_f64 v[206:207], v[206:207], s[18:19], -v[208:209]
	v_cvt_f32_f64_e32 v177, v[202:203]
	v_cvt_f32_f64_e32 v171, v[206:207]
	v_sin_f32_e32 v202, v177
	v_cos_f32_e32 v204, v177
	v_sin_f32_e32 v203, v171
	v_cos_f32_e32 v205, v171
	v_pk_mul_f32 v[210:211], v[66:67], v[174:175] op_sel_hi:[1,0]
	v_or_b32_e32 v169, 32, v167
	v_pk_mul_f32 v[208:209], v[70:71], v[174:175] op_sel_hi:[1,0]
	v_pk_mul_f32 v[210:211], v[210:211], v[114:115]
	v_lshlrev_b32_e32 v173, s7, v169
	v_pk_mul_f32 v[208:209], v[208:209], v[118:119]
	v_pk_mul_f32 v[212:213], v[210:211], v[200:201]
	v_pk_mul_f32 v[210:211], v[210:211], v[192:193]
	v_pk_mul_f32 v[214:215], v[68:69], v[174:175] op_sel_hi:[1,0]
	v_and_b32_e32 v173, 0xfff, v173
	v_lshrrev_b32_e32 v169, s5, v169
	v_pk_fma_f32 v[212:213], v[208:209], v[192:193], v[212:213]
	v_pk_fma_f32 v[208:209], v[208:209], v[200:201], v[210:211] neg_lo:[0,0,1] neg_hi:[0,0,1]
	v_pk_mul_f32 v[210:211], v[72:73], v[174:175] op_sel_hi:[1,0]
	v_pk_mul_f32 v[214:215], v[214:215], v[116:117]
	v_or3_b32 v206, v169, v173, s4
	v_pk_mul_f32 v[210:211], v[210:211], v[120:121]
	v_pk_mul_f32 v[216:217], v[214:215], v[204:205]
	v_pk_mul_f32 v[214:215], v[214:215], v[202:203]
	v_ashrrev_i32_e32 v207, 31, v206
	v_pk_fma_f32 v[216:217], v[210:211], v[202:203], v[216:217]
	v_pk_fma_f32 v[210:211], v[210:211], v[204:205], v[214:215] neg_lo:[0,0,1] neg_hi:[0,0,1]
	v_lshlrev_b64 v[206:207], 11, v[206:207]
	v_pk_mul_f32 v[212:213], v[94:95], v[212:213] op_sel_hi:[0,1]
	v_pk_mul_f32 v[208:209], v[94:95], v[208:209] op_sel_hi:[0,1]
	v_pk_mul_f32 v[216:217], v[94:95], v[216:217] op_sel_hi:[0,1]
	v_pk_mul_f32 v[210:211], v[94:95], v[210:211] op_sel_hi:[0,1]
	v_lshl_add_u64 v[206:207], v[96:97], 0, v[206:207]
	v_cvt_pk_bf16_f32 v208, v208, v209
	v_cvt_pk_bf16_f32 v209, v210, v211
	v_cvt_pk_bf16_f32 v210, v212, v213
	v_cvt_pk_bf16_f32 v211, v216, v217
	global_store_dwordx2 v[206:207], v[208:209], off nt
	global_store_dwordx2 v[206:207], v[210:211], off offset:128 nt
	v_pk_mul_f32 v[210:211], v[46:47], v[174:175] op_sel_hi:[1,0]
	v_pk_mul_f32 v[208:209], v[50:51], v[174:175] op_sel_hi:[1,0]
	v_pk_mul_f32 v[210:211], v[210:211], v[106:107]
	v_pk_mul_f32 v[208:209], v[208:209], v[110:111]
	v_pk_mul_f32 v[212:213], v[210:211], v[200:201]
	v_cvt_f32_i32_e32 v169, v175
	v_pk_fma_f32 v[212:213], v[208:209], v[192:193], v[212:213]
	v_pk_mul_f32 v[192:193], v[210:211], v[192:193]
	v_pk_mul_f32 v[212:213], v[94:95], v[212:213] op_sel_hi:[0,1]
	v_pk_fma_f32 v[192:193], v[208:209], v[200:201], v[192:193] neg_lo:[0,0,1] neg_hi:[0,0,1]
	v_pk_mul_f32 v[208:209], v[48:49], v[174:175] op_sel_hi:[1,0]
	v_pk_mul_f32 v[200:201], v[52:53], v[174:175] op_sel_hi:[1,0]
	v_pk_mul_f32 v[208:209], v[208:209], v[108:109]
	v_pk_mul_f32 v[200:201], v[200:201], v[112:113]
	v_pk_mul_f32 v[210:211], v[208:209], v[204:205]
	v_pk_mul_f32 v[192:193], v[94:95], v[192:193] op_sel_hi:[0,1]
	v_pk_fma_f32 v[210:211], v[200:201], v[202:203], v[210:211]
	v_pk_mul_f32 v[202:203], v[208:209], v[202:203]
	v_pk_mul_f32 v[210:211], v[94:95], v[210:211] op_sel_hi:[0,1]
	v_pk_fma_f32 v[200:201], v[200:201], v[204:205], v[202:203] neg_lo:[0,0,1] neg_hi:[0,0,1]
	v_cvt_pk_bf16_f32 v192, v192, v193
	v_pk_mul_f32 v[200:201], v[94:95], v[200:201] op_sel_hi:[0,1]
	v_cvt_pk_bf16_f32 v193, v200, v201
	v_mul_f32_e32 v173, v90, v169
	v_cvt_pk_bf16_f32 v200, v212, v213
	v_cvt_pk_bf16_f32 v201, v210, v211
	global_store_dwordx2 v[206:207], v[192:193], off offset:256 nt
	global_store_dwordx2 v[206:207], v[200:201], off offset:384 nt
	v_cvt_f64_f32_e32 v[192:193], v173
	v_mul_f64 v[200:201], v[192:193], s[18:19]
	v_rndne_f64_e32 v[200:201], v[200:201]
	v_fma_f64 v[192:193], v[192:193], s[18:19], -v[200:201]
	v_cvt_f32_f64_e32 v173, v[192:193]
	v_sin_f32_e32 v192, v173
	v_cos_f32_e32 v200, v173
	v_mul_f32_e32 v173, v91, v169
	v_cvt_f64_f32_e32 v[202:203], v173
	v_mul_f64 v[204:205], v[202:203], s[18:19]
	v_rndne_f64_e32 v[204:205], v[204:205]
	v_fma_f64 v[202:203], v[202:203], s[18:19], -v[204:205]
	v_cvt_f32_f64_e32 v173, v[202:203]
	v_sin_f32_e32 v193, v173
	v_cos_f32_e32 v201, v173
	v_mul_f32_e32 v173, v92, v169
	v_mul_f32_e32 v169, v93, v169
	v_cvt_f64_f32_e32 v[202:203], v173
	v_cvt_f64_f32_e32 v[206:207], v169
	v_mul_f64 v[204:205], v[202:203], s[18:19]
	v_mul_f64 v[208:209], v[206:207], s[18:19]
	v_rndne_f64_e32 v[204:205], v[204:205]
	v_rndne_f64_e32 v[208:209], v[208:209]
	v_fma_f64 v[202:203], v[202:203], s[18:19], -v[204:205]
	v_fma_f64 v[206:207], v[206:207], s[18:19], -v[208:209]
	v_cvt_f32_f64_e32 v173, v[202:203]
	v_cvt_f32_f64_e32 v169, v[206:207]
	v_sin_f32_e32 v202, v173
	v_cos_f32_e32 v204, v173
	v_sin_f32_e32 v203, v169
	v_cos_f32_e32 v205, v169
	v_pk_mul_f32 v[210:211], v[66:67], v[172:173] op_sel_hi:[1,0]
	v_or_b32_e32 v167, 48, v167
	v_pk_mul_f32 v[208:209], v[70:71], v[172:173] op_sel_hi:[1,0]
	v_pk_mul_f32 v[210:211], v[210:211], v[98:99]
	v_lshlrev_b32_e32 v171, s7, v167
	v_pk_mul_f32 v[208:209], v[208:209], v[102:103]
	v_pk_mul_f32 v[212:213], v[210:211], v[200:201]
	v_pk_mul_f32 v[210:211], v[210:211], v[192:193]
	v_pk_mul_f32 v[214:215], v[68:69], v[172:173] op_sel_hi:[1,0]
	v_and_b32_e32 v171, 0xfff, v171
	v_lshrrev_b32_e32 v167, s5, v167
	v_pk_fma_f32 v[212:213], v[208:209], v[192:193], v[212:213]
	v_pk_fma_f32 v[208:209], v[208:209], v[200:201], v[210:211] neg_lo:[0,0,1] neg_hi:[0,0,1]
	v_pk_mul_f32 v[210:211], v[72:73], v[172:173] op_sel_hi:[1,0]
	v_pk_mul_f32 v[214:215], v[214:215], v[100:101]
	v_or3_b32 v206, v167, v171, s4
	v_pk_mul_f32 v[210:211], v[210:211], v[104:105]
	v_pk_mul_f32 v[216:217], v[214:215], v[204:205]
	v_pk_mul_f32 v[214:215], v[214:215], v[202:203]
	v_ashrrev_i32_e32 v207, 31, v206
	v_pk_fma_f32 v[216:217], v[210:211], v[202:203], v[216:217]
	v_pk_fma_f32 v[210:211], v[210:211], v[204:205], v[214:215] neg_lo:[0,0,1] neg_hi:[0,0,1]
	v_lshlrev_b64 v[206:207], 11, v[206:207]
	v_pk_mul_f32 v[208:209], v[94:95], v[208:209] op_sel_hi:[0,1]
	v_pk_mul_f32 v[210:211], v[94:95], v[210:211] op_sel_hi:[0,1]
	v_lshl_add_u64 v[206:207], v[96:97], 0, v[206:207]
	v_pk_mul_f32 v[212:213], v[94:95], v[212:213] op_sel_hi:[0,1]
	v_pk_mul_f32 v[216:217], v[94:95], v[216:217] op_sel_hi:[0,1]
	v_cvt_pk_bf16_f32 v208, v208, v209
	v_cvt_pk_bf16_f32 v209, v210, v211
	v_cvt_pk_bf16_f32 v210, v212, v213
	v_cvt_pk_bf16_f32 v211, v216, v217
	global_store_dwordx2 v[206:207], v[208:209], off nt
	global_store_dwordx2 v[206:207], v[210:211], off offset:128 nt
	v_cvt_f32_i32_e32 v209, v87
	v_cvt_f32_i32_e32 v208, v86
	v_cvt_f32_i32_e32 v211, v83
	v_cvt_f32_i32_e32 v210, v82
	v_pk_mul_f32 v[212:213], v[50:51], v[172:173] op_sel_hi:[1,0]
	v_and_b32_e32 v167, 0xfcf, v123
	v_pk_mul_f32 v[208:209], v[212:213], v[208:209]
	v_pk_mul_f32 v[212:213], v[46:47], v[172:173] op_sel_hi:[1,0]
	v_cvt_f32_i32_e32 v123, v165
	v_pk_mul_f32 v[210:211], v[212:213], v[210:211]
	v_cvt_f32_i32_e32 v215, v77
	v_pk_mul_f32 v[212:213], v[210:211], v[200:201]
	v_mul_f32_e32 v171, v90, v123
	v_pk_fma_f32 v[212:213], v[208:209], v[192:193], v[212:213]
	v_pk_mul_f32 v[192:193], v[210:211], v[192:193]
	v_pk_mul_f32 v[210:211], v[52:53], v[172:173] op_sel_hi:[1,0]
	v_pk_fma_f32 v[192:193], v[208:209], v[200:201], v[192:193] neg_lo:[0,0,1] neg_hi:[0,0,1]
	v_cvt_f32_i32_e32 v201, v89
	v_cvt_f32_i32_e32 v200, v88
	v_cvt_f32_i32_e32 v209, v85
	v_cvt_f32_i32_e32 v208, v84
	v_pk_mul_f32 v[192:193], v[94:95], v[192:193] op_sel_hi:[0,1]
	v_pk_mul_f32 v[200:201], v[210:211], v[200:201]
	v_pk_mul_f32 v[210:211], v[48:49], v[172:173] op_sel_hi:[1,0]
	v_pk_mul_f32 v[212:213], v[94:95], v[212:213] op_sel_hi:[0,1]
	v_pk_mul_f32 v[208:209], v[210:211], v[208:209]
	v_cvt_pk_bf16_f32 v192, v192, v193
	v_pk_mul_f32 v[210:211], v[208:209], v[204:205]
	v_cvt_f32_i32_e32 v214, v76
	v_pk_fma_f32 v[210:211], v[200:201], v[202:203], v[210:211]
	v_pk_mul_f32 v[202:203], v[208:209], v[202:203]
	v_pk_mul_f32 v[210:211], v[94:95], v[210:211] op_sel_hi:[0,1]
	v_pk_fma_f32 v[200:201], v[200:201], v[204:205], v[202:203] neg_lo:[0,0,1] neg_hi:[0,0,1]
	v_lshlrev_b32_e32 v165, s7, v167
	v_pk_mul_f32 v[200:201], v[94:95], v[200:201] op_sel_hi:[0,1]
	v_cvt_pk_bf16_f32 v193, v200, v201
	v_cvt_pk_bf16_f32 v200, v212, v213
	v_cvt_pk_bf16_f32 v201, v210, v211
	global_store_dwordx2 v[206:207], v[192:193], off offset:256 nt
	global_store_dwordx2 v[206:207], v[200:201], off offset:384 nt
	v_cvt_f64_f32_e32 v[192:193], v171
	v_mul_f64 v[200:201], v[192:193], s[18:19]
	v_rndne_f64_e32 v[200:201], v[200:201]
	v_fma_f64 v[192:193], v[192:193], s[18:19], -v[200:201]
	v_cvt_f32_f64_e32 v171, v[192:193]
	v_sin_f32_e32 v192, v171
	v_cos_f32_e32 v200, v171
	v_mul_f32_e32 v171, v91, v123
	v_cvt_f64_f32_e32 v[202:203], v171
	v_mul_f64 v[204:205], v[202:203], s[18:19]
	v_rndne_f64_e32 v[204:205], v[204:205]
	v_fma_f64 v[202:203], v[202:203], s[18:19], -v[204:205]
	v_cvt_f32_f64_e32 v171, v[202:203]
	v_sin_f32_e32 v193, v171
	v_cos_f32_e32 v201, v171
	v_mul_f32_e32 v171, v92, v123
	v_mul_f32_e32 v123, v93, v123
	v_cvt_f64_f32_e32 v[206:207], v123
	v_cvt_f64_f32_e32 v[202:203], v171
	v_mul_f64 v[208:209], v[206:207], s[18:19]
	v_mul_f64 v[204:205], v[202:203], s[18:19]
	v_rndne_f64_e32 v[208:209], v[208:209]
	v_rndne_f64_e32 v[204:205], v[204:205]
	v_fma_f64 v[206:207], v[206:207], s[18:19], -v[208:209]
	v_cvt_f32_i32_e32 v209, v79
	v_cvt_f32_i32_e32 v208, v78
	v_fma_f64 v[202:203], v[202:203], s[18:19], -v[204:205]
	v_cvt_f32_i32_e32 v211, v75
	v_cvt_f32_i32_e32 v210, v74
	v_cvt_f32_f64_e32 v171, v[202:203]
	v_pk_mul_f32 v[212:213], v[70:71], v[170:171] op_sel_hi:[1,0]
	v_cvt_f32_f64_e32 v123, v[206:207]
	v_pk_mul_f32 v[208:209], v[212:213], v[208:209]
	v_pk_mul_f32 v[212:213], v[66:67], v[170:171] op_sel_hi:[1,0]
	v_sin_f32_e32 v202, v171
	v_pk_mul_f32 v[210:211], v[212:213], v[210:211]
	v_cos_f32_e32 v204, v171
	v_pk_mul_f32 v[212:213], v[210:211], v[200:201]
	v_pk_mul_f32 v[210:211], v[210:211], v[192:193]
	v_pk_fma_f32 v[212:213], v[208:209], v[192:193], v[212:213]
	v_pk_fma_f32 v[208:209], v[208:209], v[200:201], v[210:211] neg_lo:[0,0,1] neg_hi:[0,0,1]
	v_cvt_f32_i32_e32 v211, v81
	v_cvt_f32_i32_e32 v210, v80
	v_sin_f32_e32 v203, v123
	v_cos_f32_e32 v205, v123
	v_pk_mul_f32 v[216:217], v[72:73], v[170:171] op_sel_hi:[1,0]
	v_and_b32_e32 v165, 0xfff, v165
	v_pk_mul_f32 v[210:211], v[216:217], v[210:211]
	v_pk_mul_f32 v[216:217], v[68:69], v[170:171] op_sel_hi:[1,0]
	v_lshrrev_b32_e32 v169, s5, v167
	v_pk_mul_f32 v[214:215], v[216:217], v[214:215]
	v_or3_b32 v206, v169, v165, s4
	v_pk_mul_f32 v[216:217], v[214:215], v[204:205]
	v_pk_mul_f32 v[214:215], v[214:215], v[202:203]
	v_ashrrev_i32_e32 v207, 31, v206
	v_pk_fma_f32 v[216:217], v[210:211], v[202:203], v[216:217]
	v_pk_fma_f32 v[210:211], v[210:211], v[204:205], v[214:215] neg_lo:[0,0,1] neg_hi:[0,0,1]
	v_lshlrev_b64 v[206:207], 11, v[206:207]
	v_pk_mul_f32 v[208:209], v[94:95], v[208:209] op_sel_hi:[0,1]
	v_pk_mul_f32 v[210:211], v[94:95], v[210:211] op_sel_hi:[0,1]
	v_lshl_add_u64 v[206:207], v[96:97], 0, v[206:207]
	v_pk_mul_f32 v[212:213], v[94:95], v[212:213] op_sel_hi:[0,1]
	v_pk_mul_f32 v[216:217], v[94:95], v[216:217] op_sel_hi:[0,1]
	v_cvt_pk_bf16_f32 v208, v208, v209
	v_cvt_pk_bf16_f32 v209, v210, v211
	v_cvt_pk_bf16_f32 v210, v212, v213
	v_cvt_pk_bf16_f32 v211, v216, v217
	global_store_dwordx2 v[206:207], v[208:209], off nt
	global_store_dwordx2 v[206:207], v[210:211], off offset:128 nt
	v_cvt_f32_i32_e32 v209, v63
	v_cvt_f32_i32_e32 v208, v62
	v_cvt_f32_i32_e32 v211, v59
	v_cvt_f32_i32_e32 v210, v58
	v_pk_mul_f32 v[212:213], v[50:51], v[170:171] op_sel_hi:[1,0]
	v_cvt_f32_i32_e32 v165, v122
	v_pk_mul_f32 v[208:209], v[212:213], v[208:209]
	v_pk_mul_f32 v[212:213], v[46:47], v[170:171] op_sel_hi:[1,0]
	v_or_b32_e32 v123, 16, v167
	v_pk_mul_f32 v[210:211], v[212:213], v[210:211]
	v_lshlrev_b32_e32 v122, s7, v123
	v_pk_mul_f32 v[212:213], v[210:211], v[200:201]
	v_and_b32_e32 v169, 0xfff, v122
	v_pk_fma_f32 v[212:213], v[208:209], v[192:193], v[212:213]
	v_pk_mul_f32 v[192:193], v[210:211], v[192:193]
	v_pk_mul_f32 v[210:211], v[52:53], v[170:171] op_sel_hi:[1,0]
	v_pk_fma_f32 v[192:193], v[208:209], v[200:201], v[192:193] neg_lo:[0,0,1] neg_hi:[0,0,1]
	v_cvt_f32_i32_e32 v201, v65
	v_cvt_f32_i32_e32 v200, v64
	v_cvt_f32_i32_e32 v209, v61
	v_cvt_f32_i32_e32 v208, v60
	v_pk_mul_f32 v[192:193], v[94:95], v[192:193] op_sel_hi:[0,1]
	v_pk_mul_f32 v[200:201], v[210:211], v[200:201]
	v_pk_mul_f32 v[210:211], v[48:49], v[170:171] op_sel_hi:[1,0]
	v_mul_f32_e32 v122, v90, v165
	v_pk_mul_f32 v[208:209], v[210:211], v[208:209]
	v_pk_mul_f32 v[212:213], v[94:95], v[212:213] op_sel_hi:[0,1]
	v_pk_mul_f32 v[210:211], v[208:209], v[204:205]
	v_cvt_pk_bf16_f32 v192, v192, v193
	v_pk_fma_f32 v[210:211], v[200:201], v[202:203], v[210:211]
	v_pk_mul_f32 v[202:203], v[208:209], v[202:203]
	v_pk_mul_f32 v[210:211], v[94:95], v[210:211] op_sel_hi:[0,1]
	v_pk_fma_f32 v[200:201], v[200:201], v[204:205], v[202:203] neg_lo:[0,0,1] neg_hi:[0,0,1]
	v_lshrrev_b32_e32 v171, s5, v123
	v_pk_mul_f32 v[200:201], v[94:95], v[200:201] op_sel_hi:[0,1]
	v_cvt_pk_bf16_f32 v193, v200, v201
	v_cvt_f64_f32_e32 v[122:123], v122
	v_cvt_pk_bf16_f32 v200, v212, v213
	v_cvt_pk_bf16_f32 v201, v210, v211
	global_store_dwordx2 v[206:207], v[192:193], off offset:256 nt
	global_store_dwordx2 v[206:207], v[200:201], off offset:384 nt
	v_mul_f64 v[192:193], v[122:123], s[18:19]
	v_rndne_f64_e32 v[192:193], v[192:193]
	v_fma_f64 v[122:123], v[122:123], s[18:19], -v[192:193]
	v_cvt_f32_f64_e32 v123, v[122:123]
	v_sin_f32_e32 v122, v123
	v_cos_f32_e32 v192, v123
	v_mul_f32_e32 v123, v91, v165
	v_cvt_f64_f32_e32 v[200:201], v123
	v_mul_f64 v[202:203], v[200:201], s[18:19]
	v_rndne_f64_e32 v[202:203], v[202:203]
	v_fma_f64 v[200:201], v[200:201], s[18:19], -v[202:203]
	v_cvt_f32_f64_e32 v173, v[200:201]
	v_sin_f32_e32 v123, v173
	v_cos_f32_e32 v193, v173
	v_mul_f32_e32 v173, v92, v165
	v_mul_f32_e32 v165, v93, v165
	v_cvt_f64_f32_e32 v[204:205], v165
	v_mul_f64 v[206:207], v[204:205], s[18:19]
	v_rndne_f64_e32 v[206:207], v[206:207]
	v_fma_f64 v[204:205], v[204:205], s[18:19], -v[206:207]
	v_cvt_f32_i32_e32 v207, v55
	v_cvt_f32_i32_e32 v206, v54
	v_cvt_f32_i32_e32 v209, v43
	v_cvt_f32_i32_e32 v208, v42
	v_pk_mul_f32 v[210:211], v[70:71], v[168:169] op_sel_hi:[1,0]
	v_cvt_f64_f32_e32 v[200:201], v173
	v_pk_mul_f32 v[206:207], v[210:211], v[206:207]
	v_pk_mul_f32 v[210:211], v[66:67], v[168:169] op_sel_hi:[1,0]
	v_mul_f64 v[202:203], v[200:201], s[18:19]
	v_pk_mul_f32 v[208:209], v[210:211], v[208:209]
	v_rndne_f64_e32 v[202:203], v[202:203]
	v_pk_mul_f32 v[210:211], v[208:209], v[192:193]
	v_pk_mul_f32 v[208:209], v[208:209], v[122:123]
	v_fma_f64 v[200:201], v[200:201], s[18:19], -v[202:203]
	v_pk_fma_f32 v[210:211], v[206:207], v[122:123], v[210:211]
	v_pk_fma_f32 v[206:207], v[206:207], v[192:193], v[208:209] neg_lo:[0,0,1] neg_hi:[0,0,1]
	v_cvt_f32_i32_e32 v209, v57
	v_cvt_f32_i32_e32 v208, v56
	v_cvt_f32_f64_e32 v173, v[200:201]
	v_cvt_f32_f64_e32 v165, v[204:205]
	v_cvt_f32_i32_e32 v213, v45
	v_cvt_f32_i32_e32 v212, v44
	v_sin_f32_e32 v200, v173
	v_cos_f32_e32 v202, v173
	v_sin_f32_e32 v201, v165
	v_cos_f32_e32 v203, v165
	v_pk_mul_f32 v[214:215], v[72:73], v[168:169] op_sel_hi:[1,0]
	v_or3_b32 v204, v171, v169, s4
	v_pk_mul_f32 v[208:209], v[214:215], v[208:209]
	v_pk_mul_f32 v[214:215], v[68:69], v[168:169] op_sel_hi:[1,0]
	v_ashrrev_i32_e32 v205, 31, v204
	v_pk_mul_f32 v[212:213], v[214:215], v[212:213]
	v_lshlrev_b64 v[204:205], 11, v[204:205]
	v_pk_mul_f32 v[214:215], v[212:213], v[202:203]
	v_pk_mul_f32 v[212:213], v[212:213], v[200:201]
	v_pk_fma_f32 v[214:215], v[208:209], v[200:201], v[214:215]
	v_pk_fma_f32 v[208:209], v[208:209], v[202:203], v[212:213] neg_lo:[0,0,1] neg_hi:[0,0,1]
	v_pk_mul_f32 v[206:207], v[94:95], v[206:207] op_sel_hi:[0,1]
	v_pk_mul_f32 v[208:209], v[94:95], v[208:209] op_sel_hi:[0,1]
	v_lshl_add_u64 v[204:205], v[96:97], 0, v[204:205]
	v_pk_mul_f32 v[210:211], v[94:95], v[210:211] op_sel_hi:[0,1]
	v_pk_mul_f32 v[214:215], v[94:95], v[214:215] op_sel_hi:[0,1]
	v_cvt_pk_bf16_f32 v206, v206, v207
	v_cvt_pk_bf16_f32 v207, v208, v209
	v_cvt_pk_bf16_f32 v208, v210, v211
	v_cvt_pk_bf16_f32 v209, v214, v215
	global_store_dwordx2 v[204:205], v[206:207], off nt
	global_store_dwordx2 v[204:205], v[208:209], off offset:128 nt
	v_cvt_f32_i32_e32 v207, v39
	v_cvt_f32_i32_e32 v206, v38
	v_cvt_f32_i32_e32 v209, v35
	v_cvt_f32_i32_e32 v208, v34
	v_pk_mul_f32 v[210:211], v[50:51], v[168:169] op_sel_hi:[1,0]
	v_cvt_f32_i32_e32 v213, v29
	v_pk_mul_f32 v[206:207], v[210:211], v[206:207]
	v_pk_mul_f32 v[210:211], v[46:47], v[168:169] op_sel_hi:[1,0]
	v_cvt_f32_i32_e32 v212, v28
	v_pk_mul_f32 v[208:209], v[210:211], v[208:209]
	v_pk_mul_f32 v[214:215], v[72:73], v[166:167] op_sel_hi:[1,0]
	v_pk_mul_f32 v[210:211], v[208:209], v[192:193]
	s_nop 0
	v_pk_fma_f32 v[210:211], v[206:207], v[122:123], v[210:211]
	v_pk_mul_f32 v[122:123], v[208:209], v[122:123]
	v_pk_mul_f32 v[208:209], v[52:53], v[168:169] op_sel_hi:[1,0]
	v_pk_fma_f32 v[122:123], v[206:207], v[192:193], v[122:123] neg_lo:[0,0,1] neg_hi:[0,0,1]
	v_cvt_f32_i32_e32 v193, v41
	v_cvt_f32_i32_e32 v192, v40
	v_cvt_f32_i32_e32 v207, v37
	v_cvt_f32_i32_e32 v206, v36
	v_pk_mul_f32 v[210:211], v[94:95], v[210:211] op_sel_hi:[0,1]
	v_pk_mul_f32 v[192:193], v[208:209], v[192:193]
	v_pk_mul_f32 v[208:209], v[48:49], v[168:169] op_sel_hi:[1,0]
	v_pk_mul_f32 v[122:123], v[94:95], v[122:123] op_sel_hi:[0,1]
	v_pk_mul_f32 v[206:207], v[208:209], v[206:207]
	v_cvt_pk_bf16_f32 v122, v122, v123
	v_pk_mul_f32 v[208:209], v[206:207], v[202:203]
	s_nop 0
	v_pk_fma_f32 v[208:209], v[192:193], v[200:201], v[208:209]
	v_pk_mul_f32 v[200:201], v[206:207], v[200:201]
	v_pk_mul_f32 v[208:209], v[94:95], v[208:209] op_sel_hi:[0,1]
	v_pk_fma_f32 v[192:193], v[192:193], v[202:203], v[200:201] neg_lo:[0,0,1] neg_hi:[0,0,1]
	s_nop 0
	v_pk_mul_f32 v[192:193], v[94:95], v[192:193] op_sel_hi:[0,1]
	v_cvt_f32_i32_e32 v95, v95
	v_cvt_pk_bf16_f32 v123, v192, v193
	v_cvt_pk_bf16_f32 v192, v210, v211
	v_cvt_pk_bf16_f32 v193, v208, v209
	global_store_dwordx2 v[204:205], v[122:123], off offset:256 nt
	global_store_dwordx2 v[204:205], v[192:193], off offset:384 nt
	v_or_b32_e32 v122, 32, v167
	v_lshlrev_b32_e32 v123, s7, v122
	v_lshrrev_b32_e32 v169, s5, v122
	v_mul_f32_e32 v122, v90, v95
	v_and_b32_e32 v165, 0xfff, v123
	v_cvt_f64_f32_e32 v[122:123], v122
	v_mul_f64 v[192:193], v[122:123], s[18:19]
	v_rndne_f64_e32 v[192:193], v[192:193]
	v_fma_f64 v[122:123], v[122:123], s[18:19], -v[192:193]
	v_cvt_f32_f64_e32 v123, v[122:123]
	v_sin_f32_e32 v122, v123
	v_cos_f32_e32 v192, v123
	v_mul_f32_e32 v123, v91, v95
	v_cvt_f64_f32_e32 v[200:201], v123
	v_mul_f64 v[202:203], v[200:201], s[18:19]
	v_rndne_f64_e32 v[202:203], v[202:203]
	v_fma_f64 v[200:201], v[200:201], s[18:19], -v[202:203]
	v_cvt_f32_f64_e32 v171, v[200:201]
	v_sin_f32_e32 v123, v171
	v_cos_f32_e32 v193, v171
	v_mul_f32_e32 v171, v92, v95
	v_mul_f32_e32 v95, v93, v95
	v_cvt_f64_f32_e32 v[204:205], v95
	v_mul_f64 v[206:207], v[204:205], s[18:19]
	v_rndne_f64_e32 v[206:207], v[206:207]
	v_fma_f64 v[204:205], v[204:205], s[18:19], -v[206:207]
	v_cvt_f32_i32_e32 v207, v31
	v_cvt_f32_i32_e32 v206, v30
	v_cvt_f32_i32_e32 v209, v27
	v_cvt_f32_i32_e32 v208, v26
	v_pk_mul_f32 v[210:211], v[70:71], v[166:167] op_sel_hi:[1,0]
	v_cvt_f64_f32_e32 v[200:201], v171
	v_pk_mul_f32 v[206:207], v[210:211], v[206:207]
	v_pk_mul_f32 v[210:211], v[66:67], v[166:167] op_sel_hi:[1,0]
	v_mul_f64 v[202:203], v[200:201], s[18:19]
	v_pk_mul_f32 v[208:209], v[210:211], v[208:209]
	v_rndne_f64_e32 v[202:203], v[202:203]
	v_pk_mul_f32 v[210:211], v[208:209], v[192:193]
	v_pk_mul_f32 v[208:209], v[208:209], v[122:123]
	v_fma_f64 v[200:201], v[200:201], s[18:19], -v[202:203]
	v_pk_fma_f32 v[210:211], v[206:207], v[122:123], v[210:211]
	v_pk_fma_f32 v[206:207], v[206:207], v[192:193], v[208:209] neg_lo:[0,0,1] neg_hi:[0,0,1]
	v_cvt_f32_i32_e32 v209, v33
	v_cvt_f32_i32_e32 v208, v32
	v_cvt_f32_f64_e32 v171, v[200:201]
	v_cvt_f32_f64_e32 v95, v[204:205]
	v_sin_f32_e32 v200, v171
	v_cos_f32_e32 v202, v171
	v_sin_f32_e32 v201, v95
	v_cos_f32_e32 v203, v95
	v_pk_mul_f32 v[208:209], v[214:215], v[208:209]
	v_pk_mul_f32 v[214:215], v[68:69], v[166:167] op_sel_hi:[1,0]
	v_or3_b32 v204, v169, v165, s4
	v_pk_mul_f32 v[212:213], v[214:215], v[212:213]
	v_ashrrev_i32_e32 v205, 31, v204
	v_pk_mul_f32 v[214:215], v[212:213], v[202:203]
	v_pk_mul_f32 v[212:213], v[212:213], v[200:201]
	v_pk_fma_f32 v[214:215], v[208:209], v[200:201], v[214:215]
	v_pk_fma_f32 v[208:209], v[208:209], v[202:203], v[212:213] neg_lo:[0,0,1] neg_hi:[0,0,1]
	v_lshlrev_b64 v[204:205], 11, v[204:205]
	v_pk_mul_f32 v[206:207], v[94:95], v[206:207] op_sel_hi:[0,1]
	v_pk_mul_f32 v[208:209], v[94:95], v[208:209] op_sel_hi:[0,1]
	v_lshl_add_u64 v[204:205], v[96:97], 0, v[204:205]
	v_pk_mul_f32 v[210:211], v[94:95], v[210:211] op_sel_hi:[0,1]
	v_pk_mul_f32 v[214:215], v[94:95], v[214:215] op_sel_hi:[0,1]
	v_cvt_pk_bf16_f32 v206, v206, v207
	v_cvt_pk_bf16_f32 v207, v208, v209
	v_cvt_pk_bf16_f32 v208, v210, v211
	v_cvt_pk_bf16_f32 v209, v214, v215
	global_store_dwordx2 v[204:205], v[206:207], off nt
	global_store_dwordx2 v[204:205], v[208:209], off offset:128 nt
	v_cvt_f32_i32_e32 v207, v23
	v_cvt_f32_i32_e32 v206, v22
	v_cvt_f32_i32_e32 v209, v19
	v_cvt_f32_i32_e32 v208, v18
	v_pk_mul_f32 v[210:211], v[50:51], v[166:167] op_sel_hi:[1,0]
	v_mul_f32_e32 v90, v90, v1
	v_pk_mul_f32 v[206:207], v[210:211], v[206:207]
	v_pk_mul_f32 v[210:211], v[46:47], v[166:167] op_sel_hi:[1,0]
	v_mul_f32_e32 v91, v91, v1
	v_pk_mul_f32 v[208:209], v[210:211], v[208:209]
	v_mul_f32_e32 v92, v92, v1
	v_pk_mul_f32 v[210:211], v[208:209], v[192:193]
	v_mul_f32_e32 v1, v93, v1
	v_pk_fma_f32 v[210:211], v[206:207], v[122:123], v[210:211]
	v_pk_mul_f32 v[122:123], v[208:209], v[122:123]
	v_pk_mul_f32 v[208:209], v[52:53], v[166:167] op_sel_hi:[1,0]
	v_pk_fma_f32 v[122:123], v[206:207], v[192:193], v[122:123] neg_lo:[0,0,1] neg_hi:[0,0,1]
	v_cvt_f32_i32_e32 v193, v25
	v_cvt_f32_i32_e32 v192, v24
	v_cvt_f32_i32_e32 v207, v21
	v_cvt_f32_i32_e32 v206, v20
	v_pk_mul_f32 v[122:123], v[94:95], v[122:123] op_sel_hi:[0,1]
	v_pk_mul_f32 v[192:193], v[208:209], v[192:193]
	v_pk_mul_f32 v[208:209], v[48:49], v[166:167] op_sel_hi:[1,0]
	v_pk_mul_f32 v[210:211], v[94:95], v[210:211] op_sel_hi:[0,1]
	v_pk_mul_f32 v[206:207], v[208:209], v[206:207]
	v_cvt_pk_bf16_f32 v122, v122, v123
	v_pk_mul_f32 v[208:209], v[206:207], v[202:203]
	s_nop 0
	v_pk_fma_f32 v[208:209], v[192:193], v[200:201], v[208:209]
	v_pk_mul_f32 v[200:201], v[206:207], v[200:201]
	v_pk_mul_f32 v[208:209], v[94:95], v[208:209] op_sel_hi:[0,1]
	v_pk_fma_f32 v[192:193], v[192:193], v[202:203], v[200:201] neg_lo:[0,0,1] neg_hi:[0,0,1]
	v_cvt_f32_i32_e32 v207, v13
	v_pk_mul_f32 v[192:193], v[94:95], v[192:193] op_sel_hi:[0,1]
	v_cvt_pk_bf16_f32 v123, v192, v193
	v_or_b32_e32 v95, 48, v167
	v_cvt_pk_bf16_f32 v192, v210, v211
	v_cvt_pk_bf16_f32 v193, v208, v209
	global_store_dwordx2 v[204:205], v[122:123], off offset:256 nt
	global_store_dwordx2 v[204:205], v[192:193], off offset:384 nt
	v_lshlrev_b32_e32 v122, s7, v95
	v_and_b32_e32 v165, 0xfff, v122
	v_cvt_f64_f32_e32 v[122:123], v90
	v_mul_f64 v[192:193], v[122:123], s[18:19]
	v_rndne_f64_e32 v[192:193], v[192:193]
	v_fma_f64 v[122:123], v[122:123], s[18:19], -v[192:193]
	v_cvt_f64_f32_e32 v[192:193], v91
	v_mul_f64 v[200:201], v[192:193], s[18:19]
	v_rndne_f64_e32 v[200:201], v[200:201]
	v_fma_f64 v[192:193], v[192:193], s[18:19], -v[200:201]
	v_cvt_f32_f64_e32 v122, v[122:123]
	v_cvt_f32_f64_e32 v123, v[192:193]
	v_cvt_f64_f32_e32 v[192:193], v92
	v_mul_f64 v[200:201], v[192:193], s[18:19]
	v_rndne_f64_e32 v[200:201], v[200:201]
	v_fma_f64 v[192:193], v[192:193], s[18:19], -v[200:201]
	v_cvt_f64_f32_e32 v[200:201], v1
	v_mul_f64 v[202:203], v[200:201], s[18:19]
	v_rndne_f64_e32 v[202:203], v[202:203]
	v_lshrrev_b32_e32 v95, s5, v95
	v_fma_f64 v[200:201], v[200:201], s[18:19], -v[202:203]
	v_cvt_f32_f64_e32 v1, v[200:201]
	v_or3_b32 v200, v95, v165, s4
	v_ashrrev_i32_e32 v201, 31, v200
	v_lshlrev_b64 v[200:201], 11, v[200:201]
	v_lshl_add_u64 v[96:97], v[96:97], 0, v[200:201]
	v_cvt_f32_i32_e32 v201, v15
	v_cvt_f32_i32_e32 v200, v14
	v_cvt_f32_i32_e32 v203, v11
	v_cvt_f32_i32_e32 v202, v10
	v_sin_f32_e32 v90, v122
	v_cos_f32_e32 v122, v122
	v_sin_f32_e32 v91, v123
	v_cos_f32_e32 v123, v123
	v_pk_mul_f32 v[204:205], v[70:71], v[164:165] op_sel_hi:[1,0]
	v_cvt_f32_f64_e32 v167, v[192:193]
	v_pk_mul_f32 v[200:201], v[204:205], v[200:201]
	v_pk_mul_f32 v[204:205], v[66:67], v[164:165] op_sel_hi:[1,0]
	v_cvt_f32_i32_e32 v206, v12
	v_pk_mul_f32 v[202:203], v[204:205], v[202:203]
	v_sin_f32_e32 v92, v167
	v_pk_mul_f32 v[204:205], v[202:203], v[122:123]
	v_pk_mul_f32 v[202:203], v[202:203], v[90:91]
	v_pk_fma_f32 v[204:205], v[200:201], v[90:91], v[204:205]
	v_pk_fma_f32 v[200:201], v[200:201], v[122:123], v[202:203] neg_lo:[0,0,1] neg_hi:[0,0,1]
	v_cvt_f32_i32_e32 v203, v17
	v_cvt_f32_i32_e32 v202, v16
	v_cos_f32_e32 v192, v167
	v_sin_f32_e32 v93, v1
	v_cos_f32_e32 v193, v1
	v_pk_mul_f32 v[208:209], v[72:73], v[164:165] op_sel_hi:[1,0]
	v_pk_mul_f32 v[200:201], v[94:95], v[200:201] op_sel_hi:[0,1]
	v_pk_mul_f32 v[202:203], v[208:209], v[202:203]
	v_pk_mul_f32 v[208:209], v[68:69], v[164:165] op_sel_hi:[1,0]
	v_pk_mul_f32 v[204:205], v[94:95], v[204:205] op_sel_hi:[0,1]
	v_pk_mul_f32 v[206:207], v[208:209], v[206:207]
	v_cvt_pk_bf16_f32 v200, v200, v201
	v_pk_mul_f32 v[208:209], v[206:207], v[192:193]
	v_pk_mul_f32 v[206:207], v[206:207], v[92:93]
	v_pk_fma_f32 v[208:209], v[202:203], v[92:93], v[208:209]
	v_pk_fma_f32 v[202:203], v[202:203], v[192:193], v[206:207] neg_lo:[0,0,1] neg_hi:[0,0,1]
	v_pk_mul_f32 v[208:209], v[94:95], v[208:209] op_sel_hi:[0,1]
	v_pk_mul_f32 v[202:203], v[94:95], v[202:203] op_sel_hi:[0,1]
	v_cvt_pk_bf16_f32 v201, v202, v203
	v_cvt_pk_bf16_f32 v202, v204, v205
	v_cvt_pk_bf16_f32 v203, v208, v209
	global_store_dwordx2 v[96:97], v[200:201], off nt
	global_store_dwordx2 v[96:97], v[202:203], off offset:128 nt
	v_cvt_f32_i32_e32 v201, v7
	v_cvt_f32_i32_e32 v200, v6
	v_cvt_f32_i32_e32 v203, v3
	v_cvt_f32_i32_e32 v202, v2
	v_pk_mul_f32 v[204:205], v[50:51], v[164:165] op_sel_hi:[1,0]
	s_nop 0
	v_pk_mul_f32 v[200:201], v[204:205], v[200:201]
	v_pk_mul_f32 v[204:205], v[46:47], v[164:165] op_sel_hi:[1,0]
	s_nop 0
	v_pk_mul_f32 v[202:203], v[204:205], v[202:203]
	s_nop 0
	v_pk_mul_f32 v[204:205], v[202:203], v[122:123]
	s_nop 0
	v_pk_fma_f32 v[204:205], v[200:201], v[90:91], v[204:205]
	v_pk_mul_f32 v[90:91], v[202:203], v[90:91]
	v_pk_mul_f32 v[202:203], v[52:53], v[164:165] op_sel_hi:[1,0]
	v_pk_fma_f32 v[90:91], v[200:201], v[122:123], v[90:91] neg_lo:[0,0,1] neg_hi:[0,0,1]
	v_cvt_f32_i32_e32 v123, v9
	v_cvt_f32_i32_e32 v122, v8
	v_cvt_f32_i32_e32 v201, v5
	v_cvt_f32_i32_e32 v200, v4
	v_pk_mul_f32 v[90:91], v[94:95], v[90:91] op_sel_hi:[0,1]
	v_pk_mul_f32 v[122:123], v[202:203], v[122:123]
	v_pk_mul_f32 v[202:203], v[48:49], v[164:165] op_sel_hi:[1,0]
	v_pk_mul_f32 v[204:205], v[94:95], v[204:205] op_sel_hi:[0,1]
	v_pk_mul_f32 v[200:201], v[202:203], v[200:201]
	v_cvt_pk_bf16_f32 v90, v90, v91
	v_pk_mul_f32 v[202:203], v[200:201], v[192:193]
	s_nop 0
	v_pk_fma_f32 v[202:203], v[122:123], v[92:93], v[202:203]
	v_pk_mul_f32 v[92:93], v[200:201], v[92:93]
	v_pk_mul_f32 v[202:203], v[94:95], v[202:203] op_sel_hi:[0,1]
	v_pk_fma_f32 v[92:93], v[122:123], v[192:193], v[92:93] neg_lo:[0,0,1] neg_hi:[0,0,1]
	s_nop 0
	v_pk_mul_f32 v[92:93], v[94:95], v[92:93] op_sel_hi:[0,1]
	v_cvt_pk_bf16_f32 v91, v92, v93
	v_cvt_pk_bf16_f32 v92, v204, v205
	v_cvt_pk_bf16_f32 v93, v202, v203
	global_store_dwordx2 v[96:97], v[90:91], off offset:256 nt
	global_store_dwordx2 v[96:97], v[92:93], off offset:384 nt
	s_cbranch_execnz .LBB0_229

.LBB0_253:
	s_and_b32 s6, s23, 0xf00
	v_add_u32_e32 v97, s6, v183
	s_sub_i32 s38, 12, s21
	v_lshlrev_b32_e32 v165, s38, v97
	v_lshrrev_b32_e32 v167, s21, v97
	s_lshl_b32 s23, s31, 12
	v_and_or_b32 v165, v165, s78, v167
	v_add_u32_e32 v165, s23, v165
	v_add_u32_e32 v122, s30, v195
	v_ashrrev_i32_e32 v167, 31, v165
	v_ashrrev_i32_e32 v123, 31, v122
	v_mul_lo_u32 v167, s28, v167
	v_mul_lo_u32 v169, s29, v165
	v_mad_u64_u32 v[184:185], s[6:7], s28, v165, 0
	v_lshl_add_u64 v[122:123], v[122:123], 1, s[36:37]
	v_add3_u32 v185, v185, v167, v169
	v_mov_b32_e32 v179, v178
	v_lshl_add_u64 v[184:185], v[184:185], 1, v[122:123]
	v_cvt_pk_bf16_f32 v92, v92, v93
	v_cvt_pk_bf16_f32 v93, v94, v95
	v_cvt_pk_bf16_f32 v94, v90, v1
	v_cvt_pk_bf16_f32 v95, v96, v91
	v_mov_b32_e32 v90, v178
	v_mov_b32_e32 v91, v178
	global_store_dwordx4 v[184:185], v[92:95], off nt
	s_xor_b64 s[30:31], s[34:35], -1
	s_andn2_b64 vcc, exec, s[30:31]
	v_pk_mul_f32 v[92:93], v[52:53], v[90:91]
	v_pk_mul_f32 v[94:95], v[50:51], v[178:179]
	v_pk_mul_f32 v[180:181], v[92:93], v[180:181]
	v_pk_mul_f32 v[92:93], v[94:95], v[144:145]
	v_pk_mul_f32 v[90:91], v[48:49], v[90:91]
	v_pk_mul_f32 v[94:95], v[46:47], v[178:179]
	v_pk_mul_f32 v[142:143], v[90:91], v[142:143]
	v_pk_mul_f32 v[90:91], v[94:95], v[140:141]
	v_pk_mul_f32 v[140:141], v[92:93], s[16:17] op_sel_hi:[1,0]
	v_pk_mul_f32 v[94:95], v[180:181], s[16:17] op_sel_hi:[1,0]
	v_pk_mul_f32 v[144:145], v[142:143], s[16:17] op_sel_hi:[1,0]
	v_pk_mul_f32 v[178:179], v[90:91], s[16:17] op_sel_hi:[1,0]
	v_cndmask_b32_e64 v92, v92, v140, s[4:5]
	v_cndmask_b32_e64 v140, 0, 1, s[30:31]
	v_cndmask_b32_e64 v90, v90, v178, s[4:5]
	v_cndmask_b32_e64 v1, v91, v179, s[4:5]
	v_cndmask_b32_e64 v96, v142, v144, s[4:5]
	v_cndmask_b32_e64 v91, v143, v145, s[4:5]
	v_cndmask_b32_e64 v93, v93, v141, s[4:5]
	v_cndmask_b32_e64 v94, v180, v94, s[4:5]
	v_cndmask_b32_e64 v95, v181, v95, s[4:5]
	v_cmp_ne_u32_e64 s[6:7], 1, v140
	s_mov_b64 s[30:31], -1
	s_cbranch_vccnz .LBB0_255
	s_mov_b64 s[30:31], 0

.LBB0_257:
	v_cvt_pk_bf16_f32 v92, v92, v93
	v_cvt_pk_bf16_f32 v93, v94, v95
	v_cvt_pk_bf16_f32 v94, v90, v1
	v_cvt_pk_bf16_f32 v95, v96, v91
	v_pk_mul_f32 v[90:91], v[72:73], v[176:177] op_sel_hi:[1,0]
	global_store_dwordx4 v[184:185], v[92:95], off offset:256 nt
	s_and_b64 vcc, exec, s[6:7]
	s_mov_b64 s[30:31], -1
	v_pk_mul_f32 v[92:93], v[70:71], v[176:177] op_sel_hi:[1,0]
	v_pk_mul_f32 v[94:95], v[90:91], v[136:137]
	v_pk_mul_f32 v[90:91], v[68:69], v[176:177] op_sel_hi:[1,0]
	v_pk_mul_f32 v[136:137], v[66:67], v[176:177] op_sel_hi:[1,0]
	v_pk_mul_f32 v[92:93], v[92:93], v[138:139]
	v_pk_mul_f32 v[132:133], v[90:91], v[132:133]
	v_pk_mul_f32 v[90:91], v[136:137], v[134:135]
	v_pk_mul_f32 v[134:135], v[94:95], s[16:17] op_sel_hi:[1,0]
	v_pk_mul_f32 v[136:137], v[92:93], s[16:17] op_sel_hi:[1,0]
	v_pk_mul_f32 v[138:139], v[132:133], s[16:17] op_sel_hi:[1,0]
	v_pk_mul_f32 v[140:141], v[90:91], s[16:17] op_sel_hi:[1,0]
	v_cndmask_b32_e64 v96, v132, v138, s[4:5]
	v_cndmask_b32_e64 v90, v90, v140, s[4:5]
	v_cndmask_b32_e64 v1, v91, v141, s[4:5]
	v_cndmask_b32_e64 v91, v133, v139, s[4:5]
	v_cndmask_b32_e64 v92, v92, v136, s[4:5]
	v_cndmask_b32_e64 v93, v93, v137, s[4:5]
	v_cndmask_b32_e64 v94, v94, v134, s[4:5]
	v_cndmask_b32_e64 v95, v95, v135, s[4:5]
	s_cbranch_vccnz .LBB0_259
	s_mov_b64 s[30:31], 0

.LBB0_261:
	v_or_b32_e32 v132, 16, v97
	v_lshlrev_b32_e32 v133, s38, v132
	v_lshrrev_b32_e32 v132, s21, v132
	v_and_or_b32 v132, v133, s78, v132
	v_add_u32_e32 v132, s23, v132
	v_ashrrev_i32_e32 v133, 31, v132
	v_mul_lo_u32 v134, s28, v133
	v_mul_lo_u32 v135, s29, v132
	v_mad_u64_u32 v[132:133], s[30:31], s28, v132, 0
	v_add3_u32 v133, v133, v134, v135
	v_mov_b32_e32 v177, v176
	v_lshl_add_u64 v[132:133], v[132:133], 1, v[122:123]
	v_cvt_pk_bf16_f32 v92, v92, v93
	v_cvt_pk_bf16_f32 v93, v94, v95
	v_cvt_pk_bf16_f32 v94, v90, v1
	v_cvt_pk_bf16_f32 v95, v96, v91
	v_mov_b32_e32 v90, v176
	v_mov_b32_e32 v91, v176
	global_store_dwordx4 v[132:133], v[92:95], off nt
	s_and_b64 vcc, exec, s[6:7]
	s_mov_b64 s[30:31], -1
	v_pk_mul_f32 v[92:93], v[52:53], v[90:91]
	v_pk_mul_f32 v[94:95], v[50:51], v[176:177]
	v_pk_mul_f32 v[130:131], v[92:93], v[130:131]
	v_pk_mul_f32 v[92:93], v[94:95], v[128:129]
	v_pk_mul_f32 v[90:91], v[48:49], v[90:91]
	v_pk_mul_f32 v[94:95], v[46:47], v[176:177]
	v_pk_mul_f32 v[126:127], v[90:91], v[126:127]
	v_pk_mul_f32 v[90:91], v[94:95], v[124:125]
	v_pk_mul_f32 v[94:95], v[130:131], s[16:17] op_sel_hi:[1,0]
	v_pk_mul_f32 v[124:125], v[92:93], s[16:17] op_sel_hi:[1,0]
	v_pk_mul_f32 v[128:129], v[126:127], s[16:17] op_sel_hi:[1,0]
	v_pk_mul_f32 v[134:135], v[90:91], s[16:17] op_sel_hi:[1,0]
	v_cndmask_b32_e64 v96, v126, v128, s[4:5]
	v_cndmask_b32_e64 v90, v90, v134, s[4:5]
	v_cndmask_b32_e64 v1, v91, v135, s[4:5]
	v_cndmask_b32_e64 v91, v127, v129, s[4:5]
	v_cndmask_b32_e64 v92, v92, v124, s[4:5]
	v_cndmask_b32_e64 v93, v93, v125, s[4:5]
	v_cndmask_b32_e64 v94, v130, v94, s[4:5]
	v_cndmask_b32_e64 v95, v131, v95, s[4:5]
	s_cbranch_vccnz .LBB0_263
	s_mov_b64 s[30:31], 0

.LBB0_265:
	v_cvt_pk_bf16_f32 v92, v92, v93
	v_cvt_pk_bf16_f32 v93, v94, v95
	v_cvt_pk_bf16_f32 v94, v90, v1
	v_cvt_pk_bf16_f32 v95, v96, v91
	global_store_dwordx4 v[132:133], v[92:95], off offset:256 nt
	v_pk_mul_f32 v[90:91], v[72:73], v[174:175] op_sel_hi:[1,0]
	s_and_b64 vcc, exec, s[6:7]
	v_pk_mul_f32 v[92:93], v[70:71], v[174:175] op_sel_hi:[1,0]
	v_pk_mul_f32 v[94:95], v[90:91], v[120:121]
	v_pk_mul_f32 v[92:93], v[92:93], v[118:119]
	v_pk_mul_f32 v[90:91], v[68:69], v[174:175] op_sel_hi:[1,0]
	v_pk_mul_f32 v[118:119], v[66:67], v[174:175] op_sel_hi:[1,0]
	v_pk_mul_f32 v[116:117], v[90:91], v[116:117]
	v_pk_mul_f32 v[90:91], v[118:119], v[114:115]
	v_pk_mul_f32 v[114:115], v[94:95], s[16:17] op_sel_hi:[1,0]
	v_pk_mul_f32 v[118:119], v[92:93], s[16:17] op_sel_hi:[1,0]
	v_pk_mul_f32 v[120:121], v[116:117], s[16:17] op_sel_hi:[1,0]
	v_pk_mul_f32 v[124:125], v[90:91], s[16:17] op_sel_hi:[1,0]
	v_cndmask_b32_e64 v96, v116, v120, s[4:5]
	v_cndmask_b32_e64 v90, v90, v124, s[4:5]
	v_cndmask_b32_e64 v1, v91, v125, s[4:5]
	v_cndmask_b32_e64 v91, v117, v121, s[4:5]
	v_cndmask_b32_e64 v92, v92, v118, s[4:5]
	v_cndmask_b32_e64 v93, v93, v119, s[4:5]
	v_cndmask_b32_e64 v94, v94, v114, s[4:5]
	v_cndmask_b32_e64 v95, v95, v115, s[4:5]
	s_mov_b64 s[30:31], -1
	s_cbranch_vccnz .LBB0_267
	s_mov_b64 s[30:31], 0

.LBB0_269:
	v_or_b32_e32 v114, 32, v97
	v_lshlrev_b32_e32 v115, s38, v114
	v_lshrrev_b32_e32 v114, s21, v114
	v_and_or_b32 v114, v115, s78, v114
	v_add_u32_e32 v114, s23, v114
	v_ashrrev_i32_e32 v115, 31, v114
	v_mul_lo_u32 v116, s28, v115
	v_mul_lo_u32 v117, s29, v114
	v_mad_u64_u32 v[114:115], s[30:31], s28, v114, 0
	v_add3_u32 v115, v115, v116, v117
	v_mov_b32_e32 v175, v174
	v_lshl_add_u64 v[114:115], v[114:115], 1, v[122:123]
	v_cvt_pk_bf16_f32 v92, v92, v93
	v_cvt_pk_bf16_f32 v93, v94, v95
	v_cvt_pk_bf16_f32 v94, v90, v1
	v_cvt_pk_bf16_f32 v95, v96, v91
	v_mov_b32_e32 v90, v174
	v_mov_b32_e32 v91, v174
	global_store_dwordx4 v[114:115], v[92:95], off nt
	s_and_b64 vcc, exec, s[6:7]
	s_mov_b64 s[30:31], -1
	v_pk_mul_f32 v[92:93], v[52:53], v[90:91]
	v_pk_mul_f32 v[94:95], v[50:51], v[174:175]
	v_pk_mul_f32 v[112:113], v[92:93], v[112:113]
	v_pk_mul_f32 v[92:93], v[94:95], v[110:111]
	v_pk_mul_f32 v[90:91], v[48:49], v[90:91]
	v_pk_mul_f32 v[94:95], v[46:47], v[174:175]
	v_pk_mul_f32 v[108:109], v[90:91], v[108:109]
	v_pk_mul_f32 v[90:91], v[94:95], v[106:107]
	v_pk_mul_f32 v[94:95], v[112:113], s[16:17] op_sel_hi:[1,0]
	v_pk_mul_f32 v[106:107], v[92:93], s[16:17] op_sel_hi:[1,0]
	v_pk_mul_f32 v[110:111], v[108:109], s[16:17] op_sel_hi:[1,0]
	v_pk_mul_f32 v[116:117], v[90:91], s[16:17] op_sel_hi:[1,0]
	v_cndmask_b32_e64 v96, v108, v110, s[4:5]
	v_cndmask_b32_e64 v90, v90, v116, s[4:5]
	v_cndmask_b32_e64 v1, v91, v117, s[4:5]
	v_cndmask_b32_e64 v91, v109, v111, s[4:5]
	v_cndmask_b32_e64 v92, v92, v106, s[4:5]
	v_cndmask_b32_e64 v93, v93, v107, s[4:5]
	v_cndmask_b32_e64 v94, v112, v94, s[4:5]
	v_cndmask_b32_e64 v95, v113, v95, s[4:5]
	s_cbranch_vccnz .LBB0_271
	s_mov_b64 s[30:31], 0

.LBB0_273:
	v_cvt_pk_bf16_f32 v92, v92, v93
	v_cvt_pk_bf16_f32 v93, v94, v95
	v_cvt_pk_bf16_f32 v94, v90, v1
	v_cvt_pk_bf16_f32 v95, v96, v91
	global_store_dwordx4 v[114:115], v[92:95], off offset:256 nt
	v_pk_mul_f32 v[90:91], v[72:73], v[172:173] op_sel_hi:[1,0]
	s_and_b64 vcc, exec, s[6:7]
	v_pk_mul_f32 v[92:93], v[70:71], v[172:173] op_sel_hi:[1,0]
	v_pk_mul_f32 v[94:95], v[90:91], v[104:105]
	v_pk_mul_f32 v[92:93], v[92:93], v[102:103]
	v_pk_mul_f32 v[90:91], v[68:69], v[172:173] op_sel_hi:[1,0]
	v_pk_mul_f32 v[102:103], v[66:67], v[172:173] op_sel_hi:[1,0]
	v_pk_mul_f32 v[100:101], v[90:91], v[100:101]
	v_pk_mul_f32 v[90:91], v[102:103], v[98:99]
	v_pk_mul_f32 v[98:99], v[94:95], s[16:17] op_sel_hi:[1,0]
	v_pk_mul_f32 v[102:103], v[92:93], s[16:17] op_sel_hi:[1,0]
	v_pk_mul_f32 v[104:105], v[100:101], s[16:17] op_sel_hi:[1,0]
	v_pk_mul_f32 v[106:107], v[90:91], s[16:17] op_sel_hi:[1,0]
	v_cndmask_b32_e64 v96, v100, v104, s[4:5]
	v_cndmask_b32_e64 v90, v90, v106, s[4:5]
	v_cndmask_b32_e64 v1, v91, v107, s[4:5]
	v_cndmask_b32_e64 v91, v101, v105, s[4:5]
	v_cndmask_b32_e64 v92, v92, v102, s[4:5]
	v_cndmask_b32_e64 v93, v93, v103, s[4:5]
	v_cndmask_b32_e64 v94, v94, v98, s[4:5]
	v_cndmask_b32_e64 v95, v95, v99, s[4:5]
	s_mov_b64 s[30:31], -1
	s_cbranch_vccnz .LBB0_275
	s_mov_b64 s[30:31], 0

.LBB0_277:
	v_or_b32_e32 v98, 48, v97
	v_lshlrev_b32_e32 v99, s38, v98
	v_lshrrev_b32_e32 v98, s21, v98
	v_and_or_b32 v98, v99, s78, v98
	v_add_u32_e32 v98, s23, v98
	v_ashrrev_i32_e32 v99, 31, v98
	v_mul_lo_u32 v100, s28, v99
	v_mul_lo_u32 v101, s29, v98
	v_mad_u64_u32 v[98:99], s[30:31], s28, v98, 0
	v_cvt_f32_i32_e32 v89, v89
	v_cvt_f32_i32_e32 v88, v88
	v_add3_u32 v99, v99, v100, v101
	v_cvt_f32_i32_e32 v87, v87
	v_cvt_f32_i32_e32 v86, v86
	v_cvt_f32_i32_e32 v83, v83
	v_cvt_f32_i32_e32 v85, v85
	v_cvt_f32_i32_e32 v84, v84
	v_cvt_f32_i32_e32 v82, v82
	v_lshl_add_u64 v[98:99], v[98:99], 1, v[122:123]
	v_cvt_pk_bf16_f32 v92, v92, v93
	v_cvt_pk_bf16_f32 v93, v94, v95
	v_cvt_pk_bf16_f32 v94, v90, v1
	v_cvt_pk_bf16_f32 v95, v96, v91
	v_mov_b32_e32 v90, v172
	v_mov_b32_e32 v91, v172
	v_mov_b32_e32 v173, v172
	global_store_dwordx4 v[98:99], v[92:95], off nt
	s_and_b64 vcc, exec, s[6:7]
	s_mov_b64 s[30:31], -1
	v_pk_mul_f32 v[92:93], v[52:53], v[90:91]
	v_pk_mul_f32 v[94:95], v[50:51], v[172:173]
	v_pk_mul_f32 v[92:93], v[92:93], v[88:89]
	v_pk_mul_f32 v[88:89], v[48:49], v[90:91]
	v_pk_mul_f32 v[90:91], v[46:47], v[172:173]
	v_pk_mul_f32 v[86:87], v[94:95], v[86:87]
	v_pk_mul_f32 v[84:85], v[88:89], v[84:85]
	v_pk_mul_f32 v[82:83], v[90:91], v[82:83]
	v_pk_mul_f32 v[90:91], v[92:93], s[16:17] op_sel_hi:[1,0]
	v_pk_mul_f32 v[94:95], v[86:87], s[16:17] op_sel_hi:[1,0]
	v_pk_mul_f32 v[88:89], v[84:85], s[16:17] op_sel_hi:[1,0]
	v_pk_mul_f32 v[100:101], v[82:83], s[16:17] op_sel_hi:[1,0]
	v_cndmask_b32_e64 v88, v84, v88, s[4:5]
	v_cndmask_b32_e64 v82, v82, v100, s[4:5]
	v_cndmask_b32_e64 v1, v83, v101, s[4:5]
	v_cndmask_b32_e64 v83, v85, v89, s[4:5]
	v_cndmask_b32_e64 v84, v86, v94, s[4:5]
	v_cndmask_b32_e64 v85, v87, v95, s[4:5]
	v_cndmask_b32_e64 v86, v92, v90, s[4:5]
	v_cndmask_b32_e64 v87, v93, v91, s[4:5]
	s_cbranch_vccnz .LBB0_279
	s_mov_b64 s[30:31], 0

.LBB0_281:
	v_cvt_f32_i32_e32 v79, v79
	v_cvt_f32_i32_e32 v81, v81
	v_cvt_f32_i32_e32 v80, v80
	v_cvt_f32_i32_e32 v78, v78
	v_cvt_f32_i32_e32 v75, v75
	v_cvt_f32_i32_e32 v77, v77
	v_cvt_f32_i32_e32 v76, v76
	v_cvt_f32_i32_e32 v74, v74
	v_cvt_pk_bf16_f32 v84, v84, v85
	v_cvt_pk_bf16_f32 v85, v86, v87
	v_cvt_pk_bf16_f32 v86, v82, v1
	v_cvt_pk_bf16_f32 v87, v88, v83
	global_store_dwordx4 v[98:99], v[84:87], off offset:256 nt
	v_pk_mul_f32 v[82:83], v[72:73], v[170:171] op_sel_hi:[1,0]
	s_and_b64 vcc, exec, s[6:7]
	v_pk_mul_f32 v[84:85], v[70:71], v[170:171] op_sel_hi:[1,0]
	v_pk_mul_f32 v[82:83], v[82:83], v[80:81]
	v_pk_mul_f32 v[78:79], v[84:85], v[78:79]
	v_pk_mul_f32 v[80:81], v[68:69], v[170:171] op_sel_hi:[1,0]
	v_pk_mul_f32 v[84:85], v[66:67], v[170:171] op_sel_hi:[1,0]
	v_pk_mul_f32 v[76:77], v[80:81], v[76:77]
	v_pk_mul_f32 v[74:75], v[84:85], v[74:75]
	v_pk_mul_f32 v[84:85], v[82:83], s[16:17] op_sel_hi:[1,0]
	v_pk_mul_f32 v[86:87], v[78:79], s[16:17] op_sel_hi:[1,0]
	v_pk_mul_f32 v[80:81], v[76:77], s[16:17] op_sel_hi:[1,0]
	v_pk_mul_f32 v[88:89], v[74:75], s[16:17] op_sel_hi:[1,0]
	v_cndmask_b32_e64 v80, v76, v80, s[4:5]
	v_cndmask_b32_e64 v74, v74, v88, s[4:5]
	v_cndmask_b32_e64 v1, v75, v89, s[4:5]
	v_cndmask_b32_e64 v75, v77, v81, s[4:5]
	v_cndmask_b32_e64 v76, v78, v86, s[4:5]
	v_cndmask_b32_e64 v77, v79, v87, s[4:5]
	v_cndmask_b32_e64 v78, v82, v84, s[4:5]
	v_cndmask_b32_e64 v79, v83, v85, s[4:5]
	s_mov_b64 s[30:31], -1
	s_cbranch_vccnz .LBB0_283
	s_mov_b64 s[30:31], 0

.LBB0_285:
	v_add_u32_e32 v81, 0x80, v97
	v_lshlrev_b32_e32 v82, s38, v81
	v_lshrrev_b32_e32 v81, s21, v81
	v_and_or_b32 v81, v82, s78, v81
	v_add_u32_e32 v81, s23, v81
	v_ashrrev_i32_e32 v82, 31, v81
	v_mul_lo_u32 v84, s28, v82
	v_mul_lo_u32 v85, s29, v81
	v_mad_u64_u32 v[82:83], s[30:31], s28, v81, 0
	v_cvt_f32_i32_e32 v65, v65
	v_cvt_f32_i32_e32 v64, v64
	v_add3_u32 v83, v83, v84, v85
	v_cvt_f32_i32_e32 v63, v63
	v_cvt_f32_i32_e32 v62, v62
	v_cvt_f32_i32_e32 v59, v59
	v_cvt_f32_i32_e32 v61, v61
	v_cvt_f32_i32_e32 v60, v60
	v_cvt_f32_i32_e32 v58, v58
	v_lshl_add_u64 v[82:83], v[82:83], 1, v[122:123]
	v_cvt_pk_bf16_f32 v76, v76, v77
	v_cvt_pk_bf16_f32 v77, v78, v79
	v_cvt_pk_bf16_f32 v78, v74, v1
	v_cvt_pk_bf16_f32 v79, v80, v75
	v_mov_b32_e32 v74, v170
	v_mov_b32_e32 v75, v170
	v_mov_b32_e32 v171, v170
	global_store_dwordx4 v[82:83], v[76:79], off nt
	s_and_b64 vcc, exec, s[6:7]
	s_mov_b64 s[30:31], -1
	v_pk_mul_f32 v[76:77], v[52:53], v[74:75]
	v_pk_mul_f32 v[78:79], v[50:51], v[170:171]
	v_pk_mul_f32 v[76:77], v[76:77], v[64:65]
	v_pk_mul_f32 v[64:65], v[48:49], v[74:75]
	v_pk_mul_f32 v[74:75], v[46:47], v[170:171]
	v_pk_mul_f32 v[62:63], v[78:79], v[62:63]
	v_pk_mul_f32 v[60:61], v[64:65], v[60:61]
	v_pk_mul_f32 v[58:59], v[74:75], v[58:59]
	v_pk_mul_f32 v[74:75], v[76:77], s[16:17] op_sel_hi:[1,0]
	v_pk_mul_f32 v[78:79], v[62:63], s[16:17] op_sel_hi:[1,0]
	v_pk_mul_f32 v[64:65], v[60:61], s[16:17] op_sel_hi:[1,0]
	v_pk_mul_f32 v[80:81], v[58:59], s[16:17] op_sel_hi:[1,0]
	v_cndmask_b32_e64 v64, v60, v64, s[4:5]
	v_cndmask_b32_e64 v58, v58, v80, s[4:5]
	v_cndmask_b32_e64 v1, v59, v81, s[4:5]
	v_cndmask_b32_e64 v59, v61, v65, s[4:5]
	v_cndmask_b32_e64 v60, v62, v78, s[4:5]
	v_cndmask_b32_e64 v61, v63, v79, s[4:5]
	v_cndmask_b32_e64 v62, v76, v74, s[4:5]
	v_cndmask_b32_e64 v63, v77, v75, s[4:5]
	s_cbranch_vccnz .LBB0_287
	s_mov_b64 s[30:31], 0

.LBB0_289:
	v_cvt_f32_i32_e32 v55, v55
	v_cvt_f32_i32_e32 v57, v57
	v_cvt_f32_i32_e32 v56, v56
	v_cvt_f32_i32_e32 v54, v54
	v_cvt_f32_i32_e32 v43, v43
	v_cvt_f32_i32_e32 v45, v45
	v_cvt_f32_i32_e32 v44, v44
	v_cvt_f32_i32_e32 v42, v42
	v_cvt_pk_bf16_f32 v60, v60, v61
	v_cvt_pk_bf16_f32 v61, v62, v63
	v_cvt_pk_bf16_f32 v62, v58, v1
	v_cvt_pk_bf16_f32 v63, v64, v59
	global_store_dwordx4 v[82:83], v[60:63], off offset:256 nt
	v_pk_mul_f32 v[58:59], v[72:73], v[168:169] op_sel_hi:[1,0]
	s_and_b64 vcc, exec, s[6:7]
	v_pk_mul_f32 v[60:61], v[70:71], v[168:169] op_sel_hi:[1,0]
	v_pk_mul_f32 v[58:59], v[58:59], v[56:57]
	v_pk_mul_f32 v[54:55], v[60:61], v[54:55]
	v_pk_mul_f32 v[56:57], v[68:69], v[168:169] op_sel_hi:[1,0]
	v_pk_mul_f32 v[60:61], v[66:67], v[168:169] op_sel_hi:[1,0]
	v_pk_mul_f32 v[44:45], v[56:57], v[44:45]
	v_pk_mul_f32 v[42:43], v[60:61], v[42:43]
	v_pk_mul_f32 v[60:61], v[58:59], s[16:17] op_sel_hi:[1,0]
	v_pk_mul_f32 v[62:63], v[54:55], s[16:17] op_sel_hi:[1,0]
	v_pk_mul_f32 v[56:57], v[44:45], s[16:17] op_sel_hi:[1,0]
	v_pk_mul_f32 v[64:65], v[42:43], s[16:17] op_sel_hi:[1,0]
	v_cndmask_b32_e64 v56, v44, v56, s[4:5]
	v_cndmask_b32_e64 v42, v42, v64, s[4:5]
	v_cndmask_b32_e64 v1, v43, v65, s[4:5]
	v_cndmask_b32_e64 v43, v45, v57, s[4:5]
	v_cndmask_b32_e64 v44, v54, v62, s[4:5]
	v_cndmask_b32_e64 v45, v55, v63, s[4:5]
	v_cndmask_b32_e64 v54, v58, v60, s[4:5]
	v_cndmask_b32_e64 v55, v59, v61, s[4:5]
	s_mov_b64 s[30:31], -1
	s_cbranch_vccnz .LBB0_291
	s_mov_b64 s[30:31], 0

.LBB0_293:
	v_add_u32_e32 v57, 0x90, v97
	v_lshlrev_b32_e32 v58, s38, v57
	v_lshrrev_b32_e32 v57, s21, v57
	v_and_or_b32 v57, v58, s78, v57
	v_add_u32_e32 v57, s23, v57
	v_cvt_f32_i32_e32 v41, v41
	v_cvt_f32_i32_e32 v40, v40
	v_ashrrev_i32_e32 v58, 31, v57
	v_cvt_f32_i32_e32 v39, v39
	v_cvt_f32_i32_e32 v38, v38
	v_cvt_f32_i32_e32 v35, v35
	v_cvt_f32_i32_e32 v37, v37
	v_cvt_f32_i32_e32 v36, v36
	v_cvt_f32_i32_e32 v34, v34
	v_mul_lo_u32 v60, s28, v58
	v_mul_lo_u32 v61, s29, v57
	v_mad_u64_u32 v[58:59], s[30:31], s28, v57, 0
	v_cvt_pk_bf16_f32 v62, v42, v1
	v_cvt_pk_bf16_f32 v63, v56, v43
	v_mov_b32_e32 v42, v168
	v_mov_b32_e32 v43, v168
	v_mov_b32_e32 v169, v168
	v_add3_u32 v59, v59, v60, v61
	v_cvt_pk_bf16_f32 v60, v44, v45
	v_pk_mul_f32 v[44:45], v[52:53], v[42:43]
	v_cvt_pk_bf16_f32 v61, v54, v55
	v_pk_mul_f32 v[54:55], v[50:51], v[168:169]
	v_pk_mul_f32 v[44:45], v[44:45], v[40:41]
	v_pk_mul_f32 v[40:41], v[48:49], v[42:43]
	v_pk_mul_f32 v[42:43], v[46:47], v[168:169]
	v_pk_mul_f32 v[38:39], v[54:55], v[38:39]
	v_pk_mul_f32 v[36:37], v[40:41], v[36:37]
	v_pk_mul_f32 v[34:35], v[42:43], v[34:35]
	v_pk_mul_f32 v[42:43], v[44:45], s[16:17] op_sel_hi:[1,0]
	v_pk_mul_f32 v[54:55], v[38:39], s[16:17] op_sel_hi:[1,0]
	v_pk_mul_f32 v[40:41], v[36:37], s[16:17] op_sel_hi:[1,0]
	v_pk_mul_f32 v[56:57], v[34:35], s[16:17] op_sel_hi:[1,0]
	v_lshl_add_u64 v[58:59], v[58:59], 1, v[122:123]
	v_cndmask_b32_e64 v34, v34, v56, s[4:5]
	v_cndmask_b32_e64 v1, v35, v57, s[4:5]
	v_cndmask_b32_e64 v40, v36, v40, s[4:5]
	v_cndmask_b32_e64 v35, v37, v41, s[4:5]
	v_cndmask_b32_e64 v36, v38, v54, s[4:5]
	v_cndmask_b32_e64 v37, v39, v55, s[4:5]
	v_cndmask_b32_e64 v38, v44, v42, s[4:5]
	v_cndmask_b32_e64 v39, v45, v43, s[4:5]
	s_and_b64 vcc, exec, s[6:7]
	s_mov_b64 s[30:31], -1
	global_store_dwordx4 v[58:59], v[60:63], off nt
	s_cbranch_vccnz .LBB0_295
	s_mov_b64 s[30:31], 0

.LBB0_297:
	v_cvt_f32_i32_e32 v31, v31
	v_cvt_f32_i32_e32 v33, v33
	v_cvt_f32_i32_e32 v32, v32
	v_cvt_f32_i32_e32 v30, v30
	v_cvt_f32_i32_e32 v27, v27
	v_cvt_f32_i32_e32 v29, v29
	v_cvt_f32_i32_e32 v28, v28
	v_cvt_f32_i32_e32 v26, v26
	v_cvt_pk_bf16_f32 v36, v36, v37
	v_cvt_pk_bf16_f32 v37, v38, v39
	v_cvt_pk_bf16_f32 v38, v34, v1
	v_cvt_pk_bf16_f32 v39, v40, v35
	global_store_dwordx4 v[58:59], v[36:39], off offset:256 nt
	v_pk_mul_f32 v[34:35], v[72:73], v[166:167] op_sel_hi:[1,0]
	s_and_b64 vcc, exec, s[6:7]
	v_pk_mul_f32 v[36:37], v[70:71], v[166:167] op_sel_hi:[1,0]
	v_pk_mul_f32 v[34:35], v[34:35], v[32:33]
	v_pk_mul_f32 v[30:31], v[36:37], v[30:31]
	v_pk_mul_f32 v[32:33], v[68:69], v[166:167] op_sel_hi:[1,0]
	v_pk_mul_f32 v[36:37], v[66:67], v[166:167] op_sel_hi:[1,0]
	v_pk_mul_f32 v[28:29], v[32:33], v[28:29]
	v_pk_mul_f32 v[26:27], v[36:37], v[26:27]
	v_pk_mul_f32 v[36:37], v[34:35], s[16:17] op_sel_hi:[1,0]
	v_pk_mul_f32 v[38:39], v[30:31], s[16:17] op_sel_hi:[1,0]
	v_pk_mul_f32 v[32:33], v[28:29], s[16:17] op_sel_hi:[1,0]
	v_pk_mul_f32 v[40:41], v[26:27], s[16:17] op_sel_hi:[1,0]
	v_cndmask_b32_e64 v32, v28, v32, s[4:5]
	v_cndmask_b32_e64 v26, v26, v40, s[4:5]
	v_cndmask_b32_e64 v1, v27, v41, s[4:5]
	v_cndmask_b32_e64 v27, v29, v33, s[4:5]
	v_cndmask_b32_e64 v28, v30, v38, s[4:5]
	v_cndmask_b32_e64 v29, v31, v39, s[4:5]
	v_cndmask_b32_e64 v30, v34, v36, s[4:5]
	v_cndmask_b32_e64 v31, v35, v37, s[4:5]
	s_mov_b64 s[30:31], -1
	s_cbranch_vccnz .LBB0_299
	s_mov_b64 s[30:31], 0

.LBB0_301:
	v_add_u32_e32 v33, 0xa0, v97
	v_lshlrev_b32_e32 v34, s38, v33
	v_lshrrev_b32_e32 v33, s21, v33
	v_and_or_b32 v33, v34, s78, v33
	v_add_u32_e32 v33, s23, v33
	v_ashrrev_i32_e32 v34, 31, v33
	v_mul_lo_u32 v36, s28, v34
	v_mul_lo_u32 v37, s29, v33
	v_mad_u64_u32 v[34:35], s[30:31], s28, v33, 0
	v_cvt_f32_i32_e32 v25, v25
	v_cvt_f32_i32_e32 v24, v24
	v_add3_u32 v35, v35, v36, v37
	v_cvt_f32_i32_e32 v23, v23
	v_cvt_f32_i32_e32 v22, v22
	v_cvt_f32_i32_e32 v19, v19
	v_cvt_f32_i32_e32 v21, v21
	v_cvt_f32_i32_e32 v20, v20
	v_cvt_f32_i32_e32 v18, v18
	v_lshl_add_u64 v[34:35], v[34:35], 1, v[122:123]
	v_cvt_pk_bf16_f32 v28, v28, v29
	v_cvt_pk_bf16_f32 v29, v30, v31
	v_cvt_pk_bf16_f32 v30, v26, v1
	v_cvt_pk_bf16_f32 v31, v32, v27
	v_mov_b32_e32 v26, v166
	v_mov_b32_e32 v27, v166
	v_mov_b32_e32 v167, v166
	global_store_dwordx4 v[34:35], v[28:31], off nt
	s_and_b64 vcc, exec, s[6:7]
	s_mov_b64 s[30:31], -1
	v_pk_mul_f32 v[28:29], v[52:53], v[26:27]
	v_pk_mul_f32 v[30:31], v[50:51], v[166:167]
	v_pk_mul_f32 v[28:29], v[28:29], v[24:25]
	v_pk_mul_f32 v[24:25], v[48:49], v[26:27]
	v_pk_mul_f32 v[26:27], v[46:47], v[166:167]
	v_pk_mul_f32 v[22:23], v[30:31], v[22:23]
	v_pk_mul_f32 v[20:21], v[24:25], v[20:21]
	v_pk_mul_f32 v[18:19], v[26:27], v[18:19]
	v_pk_mul_f32 v[26:27], v[28:29], s[16:17] op_sel_hi:[1,0]
	v_pk_mul_f32 v[30:31], v[22:23], s[16:17] op_sel_hi:[1,0]
	v_pk_mul_f32 v[24:25], v[20:21], s[16:17] op_sel_hi:[1,0]
	v_pk_mul_f32 v[32:33], v[18:19], s[16:17] op_sel_hi:[1,0]
	v_cndmask_b32_e64 v24, v20, v24, s[4:5]
	v_cndmask_b32_e64 v18, v18, v32, s[4:5]
	v_cndmask_b32_e64 v1, v19, v33, s[4:5]
	v_cndmask_b32_e64 v19, v21, v25, s[4:5]
	v_cndmask_b32_e64 v20, v22, v30, s[4:5]
	v_cndmask_b32_e64 v21, v23, v31, s[4:5]
	v_cndmask_b32_e64 v22, v28, v26, s[4:5]
	v_cndmask_b32_e64 v23, v29, v27, s[4:5]
	s_cbranch_vccnz .LBB0_303
	s_mov_b64 s[30:31], 0

.LBB0_305:
	v_cvt_f32_i32_e32 v15, v15
	v_cvt_f32_i32_e32 v17, v17
	v_cvt_f32_i32_e32 v16, v16
	v_cvt_f32_i32_e32 v14, v14
	v_cvt_f32_i32_e32 v11, v11
	v_cvt_f32_i32_e32 v13, v13
	v_cvt_f32_i32_e32 v12, v12
	v_cvt_f32_i32_e32 v10, v10
	v_cvt_pk_bf16_f32 v20, v20, v21
	v_cvt_pk_bf16_f32 v21, v22, v23
	v_cvt_pk_bf16_f32 v22, v18, v1
	v_cvt_pk_bf16_f32 v23, v24, v19
	global_store_dwordx4 v[34:35], v[20:23], off offset:256 nt
	v_pk_mul_f32 v[18:19], v[72:73], v[164:165] op_sel_hi:[1,0]
	s_and_b64 vcc, exec, s[6:7]
	v_pk_mul_f32 v[20:21], v[70:71], v[164:165] op_sel_hi:[1,0]
	v_pk_mul_f32 v[18:19], v[18:19], v[16:17]
	v_pk_mul_f32 v[14:15], v[20:21], v[14:15]
	v_pk_mul_f32 v[16:17], v[68:69], v[164:165] op_sel_hi:[1,0]
	v_pk_mul_f32 v[20:21], v[66:67], v[164:165] op_sel_hi:[1,0]
	v_pk_mul_f32 v[12:13], v[16:17], v[12:13]
	v_pk_mul_f32 v[10:11], v[20:21], v[10:11]
	v_pk_mul_f32 v[20:21], v[18:19], s[16:17] op_sel_hi:[1,0]
	v_pk_mul_f32 v[22:23], v[14:15], s[16:17] op_sel_hi:[1,0]
	v_pk_mul_f32 v[16:17], v[12:13], s[16:17] op_sel_hi:[1,0]
	v_pk_mul_f32 v[24:25], v[10:11], s[16:17] op_sel_hi:[1,0]
	v_cndmask_b32_e64 v16, v12, v16, s[4:5]
	v_cndmask_b32_e64 v10, v10, v24, s[4:5]
	v_cndmask_b32_e64 v1, v11, v25, s[4:5]
	v_cndmask_b32_e64 v11, v13, v17, s[4:5]
	v_cndmask_b32_e64 v12, v14, v22, s[4:5]
	v_cndmask_b32_e64 v13, v15, v23, s[4:5]
	v_cndmask_b32_e64 v14, v18, v20, s[4:5]
	v_cndmask_b32_e64 v15, v19, v21, s[4:5]
	s_mov_b64 s[30:31], -1
	s_cbranch_vccnz .LBB0_307
	s_mov_b64 s[30:31], 0

.LBB0_309:
	v_add_u32_e32 v17, 0xb0, v97
	v_lshlrev_b32_e32 v18, s38, v17
	v_lshrrev_b32_e32 v17, s21, v17
	v_and_or_b32 v17, v18, s78, v17
	v_add_u32_e32 v17, s23, v17
	v_ashrrev_i32_e32 v18, 31, v17
	v_mul_lo_u32 v20, s28, v18
	v_mul_lo_u32 v21, s29, v17
	v_mad_u64_u32 v[18:19], s[28:29], s28, v17, 0
	v_cvt_f32_i32_e32 v9, v9
	v_cvt_f32_i32_e32 v8, v8
	v_add3_u32 v19, v19, v20, v21
	v_cvt_f32_i32_e32 v7, v7
	v_cvt_f32_i32_e32 v6, v6
	v_cvt_f32_i32_e32 v3, v3
	v_cvt_f32_i32_e32 v5, v5
	v_cvt_f32_i32_e32 v4, v4
	v_cvt_f32_i32_e32 v2, v2
	v_lshl_add_u64 v[18:19], v[18:19], 1, v[122:123]
	v_cvt_pk_bf16_f32 v12, v12, v13
	v_cvt_pk_bf16_f32 v13, v14, v15
	v_cvt_pk_bf16_f32 v14, v10, v1
	v_cvt_pk_bf16_f32 v15, v16, v11
	v_mov_b32_e32 v10, v164
	v_mov_b32_e32 v11, v164
	v_mov_b32_e32 v165, v164
	global_store_dwordx4 v[18:19], v[12:15], off nt
	s_and_b64 vcc, exec, s[6:7]
	s_nop 0
	v_pk_mul_f32 v[12:13], v[52:53], v[10:11]
	v_pk_mul_f32 v[14:15], v[50:51], v[164:165]
	v_pk_mul_f32 v[12:13], v[12:13], v[8:9]
	v_pk_mul_f32 v[8:9], v[48:49], v[10:11]
	v_pk_mul_f32 v[10:11], v[46:47], v[164:165]
	v_pk_mul_f32 v[6:7], v[14:15], v[6:7]
	v_pk_mul_f32 v[4:5], v[8:9], v[4:5]
	v_pk_mul_f32 v[2:3], v[10:11], v[2:3]
	v_pk_mul_f32 v[10:11], v[12:13], s[16:17] op_sel_hi:[1,0]
	v_pk_mul_f32 v[14:15], v[6:7], s[16:17] op_sel_hi:[1,0]
	v_pk_mul_f32 v[8:9], v[4:5], s[16:17] op_sel_hi:[1,0]
	v_pk_mul_f32 v[16:17], v[2:3], s[16:17] op_sel_hi:[1,0]
	v_cndmask_b32_e64 v8, v4, v8, s[4:5]
	v_cndmask_b32_e64 v2, v2, v16, s[4:5]
	v_cndmask_b32_e64 v1, v3, v17, s[4:5]
	v_cndmask_b32_e64 v3, v5, v9, s[4:5]
	v_cndmask_b32_e64 v4, v6, v14, s[4:5]
	v_cndmask_b32_e64 v5, v7, v15, s[4:5]
	v_cndmask_b32_e64 v6, v12, v10, s[4:5]
	v_cndmask_b32_e64 v7, v13, v11, s[4:5]
	s_mov_b64 s[4:5], -1
	s_cbranch_vccnz .LBB0_311
	s_mov_b64 s[4:5], 0

.LBB0_313:
	v_cvt_pk_bf16_f32 v4, v4, v5
	v_cvt_pk_bf16_f32 v5, v6, v7
	v_cvt_pk_bf16_f32 v6, v2, v1
	v_cvt_pk_bf16_f32 v7, v8, v3
	global_store_dwordx4 v[18:19], v[4:7], off offset:256 nt
	s_andn2_b64 vcc, exec, s[2:3]
	s_mov_b64 s[2:3], -1
	s_cbranch_vccnz .LBB0_220

.LBB0_851:
	s_lshl_b32 s30, s57, 8
	v_lshl_add_u32 v176, s28, 8, v170
	s_ashr_i32 s31, s30, 31
	v_ashrrev_i32_e32 v177, 31, v176
	v_lshl_add_u64 v[106:107], s[30:31], 2, v[150:151]
	v_lshl_add_u64 v[178:179], v[176:177], 2, s[4:5]
	global_load_dword v180, v[178:179], off
	global_load_dwordx4 v[126:129], v[106:107], off
	global_load_dwordx4 v[122:125], v[106:107], off offset:64
	global_load_dwordx4 v[110:113], v[106:107], off offset:512
	s_nop 0
	global_load_dwordx4 v[106:109], v[106:107], off offset:576
	v_or_b32_e32 v196, 16, v176
	v_ashrrev_i32_e32 v197, 31, v196
	v_cvt_f32_i32_e32 v193, v135
	v_cvt_f32_i32_e32 v192, v134
	v_lshl_add_u64 v[134:135], v[196:197], 2, s[4:5]
	global_load_dword v198, v[134:135], off
	v_or_b32_e32 v204, 32, v176
	v_cvt_f32_i32_e32 v184, v142
	v_cvt_f32_i32_e32 v200, v130
	v_or_b32_e32 v130, s30, v172
	v_or_b32_e32 v142, 48, v176
	v_ashrrev_i32_e32 v205, 31, v204
	v_cvt_f32_i32_e32 v185, v143
	v_cvt_f32_i32_e32 v191, v141
	v_cvt_f32_i32_e32 v190, v140
	v_cvt_f32_i32_e32 v201, v131
	v_ashrrev_i32_e32 v131, 31, v130
	v_ashrrev_i32_e32 v143, 31, v142
	v_lshl_add_u64 v[140:141], v[204:205], 2, s[4:5]
	v_cvt_f32_i32_e32 v187, v145
	v_cvt_f32_i32_e32 v186, v144
	v_cvt_f32_i32_e32 v188, v138
	v_cvt_f32_i32_e32 v194, v136
	v_cvt_f32_i32_e32 v203, v133
	v_cvt_f32_i32_e32 v202, v132
	v_lshlrev_b64 v[132:133], 15, v[176:177]
	v_lshl_add_u64 v[176:177], v[142:143], 2, s[4:5]
	v_lshlrev_b64 v[144:145], 1, v[130:131]
	global_load_dword v138, v[178:179], off offset:512
	global_load_dword v136, v[178:179], off offset:576
	global_load_dword v134, v[178:179], off offset:640
	global_load_dword v160, v[140:141], off
	s_nop 0
	global_load_dword v140, v[176:177], off
	global_load_dword v130, v[178:179], off offset:704
	v_cvt_f32_i32_e32 v189, v139
	v_cvt_f32_i32_e32 v195, v137
	v_lshl_add_u64 v[132:133], s[48:49], 0, v[132:133]
	v_lshl_add_u64 v[132:133], v[132:133], 0, v[144:145]
	v_cvt_f32_i32_e32 v119, v119
	v_cvt_f32_i32_e32 v118, v118
	v_cvt_f32_i32_e32 v121, v121
	v_cvt_f32_i32_e32 v120, v120
	v_cvt_f32_i32_e32 v115, v115
	v_cvt_f32_i32_e32 v114, v114
	v_cvt_f32_i32_e32 v117, v117
	v_cvt_f32_i32_e32 v116, v116
	v_cvt_f32_i32_e32 v103, v103
	v_cvt_f32_i32_e32 v102, v102
	v_cvt_f32_i32_e32 v105, v105
	v_cvt_f32_i32_e32 v104, v104
	v_cvt_f32_i32_e32 v99, v99
	v_cvt_f32_i32_e32 v98, v98
	v_cvt_f32_i32_e32 v101, v101
	v_cvt_f32_i32_e32 v100, v100
	v_cvt_f32_i32_e32 v95, v95
	v_cvt_f32_i32_e32 v94, v94
	v_cvt_f32_i32_e32 v97, v97
	v_cvt_f32_i32_e32 v96, v96
	v_cvt_f32_i32_e32 v91, v91
	v_cvt_f32_i32_e32 v90, v90
	v_cvt_f32_i32_e32 v93, v93
	v_cvt_f32_i32_e32 v92, v92
	v_cvt_f32_i32_e32 v87, v87
	v_cvt_f32_i32_e32 v86, v86
	v_cvt_f32_i32_e32 v89, v89
	v_cvt_f32_i32_e32 v88, v88
	v_cvt_f32_i32_e32 v83, v83
	v_cvt_f32_i32_e32 v82, v82
	v_cvt_f32_i32_e32 v85, v85
	v_cvt_f32_i32_e32 v84, v84
	v_cvt_f32_i32_e32 v79, v79
	v_cvt_f32_i32_e32 v78, v78
	v_cvt_f32_i32_e32 v81, v81
	v_cvt_f32_i32_e32 v80, v80
	v_cvt_f32_i32_e32 v75, v75
	v_cvt_f32_i32_e32 v74, v74
	v_cvt_f32_i32_e32 v77, v77
	v_cvt_f32_i32_e32 v76, v76
	v_cvt_f32_i32_e32 v71, v71
	v_cvt_f32_i32_e32 v70, v70
	v_cvt_f32_i32_e32 v73, v73
	s_waitcnt vmcnt(0)
	v_pk_mul_f32 v[176:177], v[128:129], v[180:181] op_sel_hi:[1,0]
	v_pk_mul_f32 v[178:179], v[126:127], v[180:181] op_sel_hi:[1,0]
	v_pk_mul_f32 v[206:207], v[124:125], v[180:181] op_sel_hi:[1,0]
	v_pk_mul_f32 v[208:209], v[122:123], v[180:181] op_sel_hi:[1,0]
	v_pk_mul_f32 v[176:177], v[176:177], v[186:187]
	v_pk_mul_f32 v[178:179], v[178:179], v[184:185]
	v_pk_mul_f32 v[184:185], v[206:207], v[190:191]
	v_pk_mul_f32 v[186:187], v[208:209], v[188:189]
	v_pk_mul_f32 v[210:211], v[112:113], v[180:181] op_sel_hi:[1,0]
	v_max_f32_e32 v178, 0, v178
	v_max_f32_e32 v186, 0, v186
	v_max_f32_e32 v179, 0, v179
	v_max_f32_e32 v187, 0, v187
	v_max_f32_e32 v176, 0, v176
	v_max_f32_e32 v184, 0, v184
	v_max_f32_e32 v177, 0, v177
	v_max_f32_e32 v185, 0, v185
	v_pk_mul_f32 v[212:213], v[110:111], v[180:181] op_sel_hi:[1,0]
	v_pk_mul_f32 v[214:215], v[108:109], v[180:181] op_sel_hi:[1,0]
	v_pk_mul_f32 v[180:181], v[106:107], v[180:181] op_sel_hi:[1,0]
	v_pk_mul_f32 v[188:189], v[210:211], v[194:195]
	v_pk_mul_f32 v[178:179], v[178:179], v[178:179]
	v_pk_mul_f32 v[186:187], v[186:187], v[186:187]
	v_pk_mul_f32 v[194:195], v[176:177], v[176:177]
	v_pk_mul_f32 v[184:185], v[184:185], v[184:185]
	v_pk_mul_f32 v[190:191], v[212:213], v[192:193]
	v_pk_mul_f32 v[192:193], v[214:215], v[202:203]
	v_pk_mul_f32 v[180:181], v[180:181], v[200:201]
	v_cvt_pk_bf16_f32 v176, v178, v179
	v_cvt_pk_bf16_f32 v177, v194, v195
	v_cvt_pk_bf16_f32 v178, v186, v187
	v_cvt_pk_bf16_f32 v179, v184, v185
	v_max_f32_e32 v190, 0, v190
	v_max_f32_e32 v180, 0, v180
	v_max_f32_e32 v191, 0, v191
	v_max_f32_e32 v181, 0, v181
	v_max_f32_e32 v188, 0, v188
	global_store_dwordx4 v[132:133], v[176:179], off nt
	v_max_f32_e32 v189, 0, v189
	v_pk_mul_f32 v[190:191], v[190:191], v[190:191]
	v_max_f32_e32 v176, 0, v192
	v_max_f32_e32 v177, 0, v193
	v_pk_mul_f32 v[180:181], v[180:181], v[180:181]
	v_pk_mul_f32 v[178:179], v[188:189], v[188:189]
	v_pk_mul_f32 v[184:185], v[176:177], v[176:177]
	v_cvt_pk_bf16_f32 v176, v190, v191
	v_cvt_pk_bf16_f32 v177, v178, v179
	v_cvt_pk_bf16_f32 v178, v180, v181
	v_cvt_pk_bf16_f32 v179, v184, v185
	v_pk_mul_f32 v[180:181], v[126:127], v[198:199] op_sel_hi:[1,0]
	global_store_dwordx4 v[132:133], v[176:179], off offset:256 nt
	v_pk_mul_f32 v[118:119], v[180:181], v[118:119]
	v_pk_mul_f32 v[180:181], v[122:123], v[198:199] op_sel_hi:[1,0]
	v_pk_mul_f32 v[178:179], v[128:129], v[198:199] op_sel_hi:[1,0]
	v_pk_mul_f32 v[114:115], v[180:181], v[114:115]
	v_pk_mul_f32 v[120:121], v[178:179], v[120:121]
	v_pk_mul_f32 v[178:179], v[124:125], v[198:199] op_sel_hi:[1,0]
	v_max_f32_e32 v114, 0, v114
	v_pk_mul_f32 v[116:117], v[178:179], v[116:117]
	v_max_f32_e32 v115, 0, v115
	v_lshlrev_b64 v[176:177], 15, v[196:197]
	v_max_f32_e32 v118, 0, v118
	v_max_f32_e32 v119, 0, v119
	v_pk_mul_f32 v[178:179], v[114:115], v[114:115]
	v_max_f32_e32 v114, 0, v120
	v_max_f32_e32 v116, 0, v116
	v_max_f32_e32 v115, 0, v121
	v_max_f32_e32 v117, 0, v117
	v_lshl_add_u64 v[176:177], s[48:49], 0, v[176:177]
	v_pk_mul_f32 v[118:119], v[118:119], v[118:119]
	v_pk_mul_f32 v[120:121], v[114:115], v[114:115]
	v_pk_mul_f32 v[180:181], v[116:117], v[116:117]
	v_lshl_add_u64 v[176:177], v[176:177], 0, v[144:145]
	v_cvt_pk_bf16_f32 v114, v118, v119
	v_cvt_pk_bf16_f32 v115, v120, v121
	v_cvt_pk_bf16_f32 v116, v178, v179
	v_cvt_pk_bf16_f32 v117, v180, v181
	global_store_dwordx4 v[176:177], v[114:117], off nt
	v_cvt_f32_i32_e32 v72, v72
	v_cvt_f32_i32_e32 v67, v67
	v_pk_mul_f32 v[116:117], v[110:111], v[198:199] op_sel_hi:[1,0]
	v_pk_mul_f32 v[114:115], v[112:113], v[198:199] op_sel_hi:[1,0]
	v_pk_mul_f32 v[102:103], v[116:117], v[102:103]
	v_pk_mul_f32 v[116:117], v[106:107], v[198:199] op_sel_hi:[1,0]
	v_pk_mul_f32 v[104:105], v[114:115], v[104:105]
	v_pk_mul_f32 v[114:115], v[108:109], v[198:199] op_sel_hi:[1,0]
	v_pk_mul_f32 v[98:99], v[116:117], v[98:99]
	v_pk_mul_f32 v[100:101], v[114:115], v[100:101]
	v_max_f32_e32 v98, 0, v98
	v_max_f32_e32 v99, 0, v99
	v_max_f32_e32 v102, 0, v102
	v_max_f32_e32 v103, 0, v103
	v_pk_mul_f32 v[114:115], v[98:99], v[98:99]
	v_max_f32_e32 v98, 0, v104
	v_max_f32_e32 v100, 0, v100
	v_max_f32_e32 v99, 0, v105
	v_max_f32_e32 v101, 0, v101
	v_pk_mul_f32 v[102:103], v[102:103], v[102:103]
	v_pk_mul_f32 v[104:105], v[98:99], v[98:99]
	v_pk_mul_f32 v[116:117], v[100:101], v[100:101]
	v_cvt_pk_bf16_f32 v98, v102, v103
	v_cvt_pk_bf16_f32 v99, v104, v105
	v_cvt_pk_bf16_f32 v100, v114, v115
	v_cvt_pk_bf16_f32 v101, v116, v117
	v_pk_mul_f32 v[102:103], v[126:127], v[160:161] op_sel_hi:[1,0]
	global_store_dwordx4 v[176:177], v[98:101], off offset:256 nt
	v_pk_mul_f32 v[94:95], v[102:103], v[94:95]
	v_pk_mul_f32 v[102:103], v[122:123], v[160:161] op_sel_hi:[1,0]
	v_pk_mul_f32 v[100:101], v[128:129], v[160:161] op_sel_hi:[1,0]
	v_pk_mul_f32 v[90:91], v[102:103], v[90:91]
	v_pk_mul_f32 v[96:97], v[100:101], v[96:97]
	v_pk_mul_f32 v[100:101], v[124:125], v[160:161] op_sel_hi:[1,0]
	v_max_f32_e32 v90, 0, v90
	v_pk_mul_f32 v[92:93], v[100:101], v[92:93]
	v_max_f32_e32 v91, 0, v91
	v_lshlrev_b64 v[98:99], 15, v[204:205]
	v_max_f32_e32 v94, 0, v94
	v_max_f32_e32 v95, 0, v95
	v_pk_mul_f32 v[100:101], v[90:91], v[90:91]
	v_max_f32_e32 v90, 0, v96
	v_max_f32_e32 v92, 0, v92
	v_max_f32_e32 v91, 0, v97
	v_max_f32_e32 v93, 0, v93
	v_lshl_add_u64 v[98:99], s[48:49], 0, v[98:99]
	v_pk_mul_f32 v[94:95], v[94:95], v[94:95]
	v_pk_mul_f32 v[96:97], v[90:91], v[90:91]
	v_pk_mul_f32 v[102:103], v[92:93], v[92:93]
	v_lshl_add_u64 v[98:99], v[98:99], 0, v[144:145]
	v_cvt_pk_bf16_f32 v90, v94, v95
	v_cvt_pk_bf16_f32 v91, v96, v97
	v_cvt_pk_bf16_f32 v92, v100, v101
	v_cvt_pk_bf16_f32 v93, v102, v103
	global_store_dwordx4 v[98:99], v[90:93], off nt
	v_cvt_f32_i32_e32 v66, v66
	v_cvt_f32_i32_e32 v69, v69
	v_pk_mul_f32 v[92:93], v[110:111], v[160:161] op_sel_hi:[1,0]
	v_pk_mul_f32 v[90:91], v[112:113], v[160:161] op_sel_hi:[1,0]
	v_pk_mul_f32 v[86:87], v[92:93], v[86:87]
	v_pk_mul_f32 v[92:93], v[106:107], v[160:161] op_sel_hi:[1,0]
	v_pk_mul_f32 v[88:89], v[90:91], v[88:89]
	v_pk_mul_f32 v[90:91], v[108:109], v[160:161] op_sel_hi:[1,0]
	v_pk_mul_f32 v[82:83], v[92:93], v[82:83]
	v_pk_mul_f32 v[84:85], v[90:91], v[84:85]
	v_max_f32_e32 v82, 0, v82
	v_max_f32_e32 v83, 0, v83
	v_max_f32_e32 v86, 0, v86
	v_max_f32_e32 v87, 0, v87
	v_pk_mul_f32 v[90:91], v[82:83], v[82:83]
	v_max_f32_e32 v82, 0, v88
	v_max_f32_e32 v84, 0, v84
	v_max_f32_e32 v83, 0, v89
	v_max_f32_e32 v85, 0, v85
	v_pk_mul_f32 v[86:87], v[86:87], v[86:87]
	v_pk_mul_f32 v[88:89], v[82:83], v[82:83]
	v_pk_mul_f32 v[92:93], v[84:85], v[84:85]
	v_cvt_pk_bf16_f32 v82, v86, v87
	v_cvt_pk_bf16_f32 v83, v88, v89
	v_cvt_pk_bf16_f32 v84, v90, v91
	v_cvt_pk_bf16_f32 v85, v92, v93
	v_pk_mul_f32 v[86:87], v[126:127], v[140:141] op_sel_hi:[1,0]
	global_store_dwordx4 v[98:99], v[82:85], off offset:256 nt
	v_pk_mul_f32 v[78:79], v[86:87], v[78:79]
	v_pk_mul_f32 v[86:87], v[122:123], v[140:141] op_sel_hi:[1,0]
	v_pk_mul_f32 v[84:85], v[128:129], v[140:141] op_sel_hi:[1,0]
	v_pk_mul_f32 v[74:75], v[86:87], v[74:75]
	v_pk_mul_f32 v[80:81], v[84:85], v[80:81]
	v_pk_mul_f32 v[84:85], v[124:125], v[140:141] op_sel_hi:[1,0]
	v_max_f32_e32 v74, 0, v74
	v_pk_mul_f32 v[76:77], v[84:85], v[76:77]
	v_max_f32_e32 v75, 0, v75
	v_lshlrev_b64 v[82:83], 15, v[142:143]
	v_max_f32_e32 v78, 0, v78
	v_max_f32_e32 v79, 0, v79
	v_pk_mul_f32 v[84:85], v[74:75], v[74:75]
	v_max_f32_e32 v74, 0, v80
	v_max_f32_e32 v76, 0, v76
	v_max_f32_e32 v75, 0, v81
	v_max_f32_e32 v77, 0, v77
	v_lshl_add_u64 v[82:83], s[48:49], 0, v[82:83]
	v_pk_mul_f32 v[78:79], v[78:79], v[78:79]
	v_pk_mul_f32 v[80:81], v[74:75], v[74:75]
	v_pk_mul_f32 v[86:87], v[76:77], v[76:77]
	v_lshl_add_u64 v[82:83], v[82:83], 0, v[144:145]
	v_cvt_pk_bf16_f32 v74, v78, v79
	v_cvt_pk_bf16_f32 v75, v80, v81
	v_cvt_pk_bf16_f32 v76, v84, v85
	v_cvt_pk_bf16_f32 v77, v86, v87
	v_cvt_f32_i32_e32 v68, v68
	global_store_dwordx4 v[82:83], v[74:77], off nt
	v_cvt_f32_i32_e32 v63, v63
	v_cvt_f32_i32_e32 v62, v62
	v_pk_mul_f32 v[76:77], v[110:111], v[140:141] op_sel_hi:[1,0]
	v_pk_mul_f32 v[74:75], v[112:113], v[140:141] op_sel_hi:[1,0]
	v_pk_mul_f32 v[70:71], v[76:77], v[70:71]
	v_pk_mul_f32 v[76:77], v[106:107], v[140:141] op_sel_hi:[1,0]
	v_pk_mul_f32 v[72:73], v[74:75], v[72:73]
	v_pk_mul_f32 v[74:75], v[108:109], v[140:141] op_sel_hi:[1,0]
	v_pk_mul_f32 v[66:67], v[76:77], v[66:67]
	v_pk_mul_f32 v[68:69], v[74:75], v[68:69]
	v_max_f32_e32 v66, 0, v66
	v_max_f32_e32 v67, 0, v67
	v_max_f32_e32 v70, 0, v70
	v_max_f32_e32 v71, 0, v71
	v_pk_mul_f32 v[74:75], v[66:67], v[66:67]
	v_max_f32_e32 v66, 0, v72
	v_max_f32_e32 v68, 0, v68
	v_max_f32_e32 v67, 0, v73
	v_max_f32_e32 v69, 0, v69
	v_cvt_f32_i32_e32 v65, v65
	v_cvt_f32_i32_e32 v64, v64
	v_cvt_f32_i32_e32 v59, v59
	v_cvt_f32_i32_e32 v58, v58
	v_pk_mul_f32 v[70:71], v[70:71], v[70:71]
	v_pk_mul_f32 v[72:73], v[66:67], v[66:67]
	v_pk_mul_f32 v[76:77], v[68:69], v[68:69]
	v_cvt_f32_i32_e32 v61, v61
	v_cvt_f32_i32_e32 v60, v60
	v_cvt_pk_bf16_f32 v66, v70, v71
	v_cvt_pk_bf16_f32 v67, v72, v73
	v_cvt_pk_bf16_f32 v68, v74, v75
	v_cvt_pk_bf16_f32 v69, v76, v77
	v_pk_mul_f32 v[70:71], v[126:127], v[138:139] op_sel_hi:[1,0]
	global_store_dwordx4 v[82:83], v[66:69], off offset:256 nt
	v_pk_mul_f32 v[62:63], v[70:71], v[62:63]
	v_pk_mul_f32 v[70:71], v[122:123], v[138:139] op_sel_hi:[1,0]
	v_pk_mul_f32 v[68:69], v[128:129], v[138:139] op_sel_hi:[1,0]
	v_pk_mul_f32 v[58:59], v[70:71], v[58:59]
	v_pk_mul_f32 v[64:65], v[68:69], v[64:65]
	v_pk_mul_f32 v[68:69], v[124:125], v[138:139] op_sel_hi:[1,0]
	v_max_f32_e32 v62, 0, v62
	v_pk_mul_f32 v[60:61], v[68:69], v[60:61]
	v_max_f32_e32 v58, 0, v58
	v_max_f32_e32 v63, 0, v63
	v_max_f32_e32 v59, 0, v59
	v_pk_mul_f32 v[62:63], v[62:63], v[62:63]
	v_pk_mul_f32 v[68:69], v[58:59], v[58:59]
	v_max_f32_e32 v58, 0, v64
	v_max_f32_e32 v60, 0, v60
	v_max_f32_e32 v59, 0, v65
	v_max_f32_e32 v61, 0, v61
	v_cvt_f32_i32_e32 v55, v55
	v_cvt_f32_i32_e32 v54, v54
	v_pk_mul_f32 v[64:65], v[58:59], v[58:59]
	v_pk_mul_f32 v[70:71], v[60:61], v[60:61]
	v_cvt_pk_bf16_f32 v58, v62, v63
	v_add_co_u32_e32 v62, vcc, s53, v132
	v_cvt_f32_i32_e32 v57, v57
	v_cvt_f32_i32_e32 v56, v56
	v_cvt_f32_i32_e32 v51, v51
	v_cvt_f32_i32_e32 v50, v50
	v_cvt_pk_bf16_f32 v59, v64, v65
	v_cvt_pk_bf16_f32 v60, v68, v69
	v_cvt_pk_bf16_f32 v61, v70, v71
	v_addc_co_u32_e32 v63, vcc, 0, v133, vcc
	v_cvt_f32_i32_e32 v53, v53
	v_cvt_f32_i32_e32 v52, v52
	global_store_dwordx4 v[62:63], v[58:61], off nt
	v_cvt_f32_i32_e32 v47, v47
	v_cvt_f32_i32_e32 v46, v46
	v_pk_mul_f32 v[60:61], v[110:111], v[138:139] op_sel_hi:[1,0]
	v_pk_mul_f32 v[58:59], v[112:113], v[138:139] op_sel_hi:[1,0]
	v_pk_mul_f32 v[54:55], v[60:61], v[54:55]
	v_pk_mul_f32 v[60:61], v[106:107], v[138:139] op_sel_hi:[1,0]
	v_pk_mul_f32 v[56:57], v[58:59], v[56:57]
	v_pk_mul_f32 v[58:59], v[108:109], v[138:139] op_sel_hi:[1,0]
	v_pk_mul_f32 v[50:51], v[60:61], v[50:51]
	v_pk_mul_f32 v[52:53], v[58:59], v[52:53]
	v_max_f32_e32 v50, 0, v50
	v_max_f32_e32 v51, 0, v51
	v_max_f32_e32 v54, 0, v54
	v_max_f32_e32 v55, 0, v55
	v_pk_mul_f32 v[58:59], v[50:51], v[50:51]
	v_max_f32_e32 v50, 0, v56
	v_max_f32_e32 v52, 0, v52
	v_max_f32_e32 v51, 0, v57
	v_max_f32_e32 v53, 0, v53
	v_cvt_f32_i32_e32 v49, v49
	v_cvt_f32_i32_e32 v48, v48
	v_cvt_f32_i32_e32 v43, v43
	v_cvt_f32_i32_e32 v42, v42
	v_pk_mul_f32 v[54:55], v[54:55], v[54:55]
	v_pk_mul_f32 v[56:57], v[50:51], v[50:51]
	v_pk_mul_f32 v[60:61], v[52:53], v[52:53]
	v_cvt_f32_i32_e32 v45, v45
	v_cvt_f32_i32_e32 v44, v44
	v_lshl_add_u64 v[66:67], v[132:133], 0, s[10:11]
	v_cvt_pk_bf16_f32 v50, v54, v55
	v_cvt_pk_bf16_f32 v51, v56, v57
	v_cvt_pk_bf16_f32 v52, v58, v59
	v_cvt_pk_bf16_f32 v53, v60, v61
	v_pk_mul_f32 v[54:55], v[126:127], v[136:137] op_sel_hi:[1,0]
	global_store_dwordx4 v[66:67], v[50:53], off offset:256 nt
	v_pk_mul_f32 v[46:47], v[54:55], v[46:47]
	v_pk_mul_f32 v[54:55], v[122:123], v[136:137] op_sel_hi:[1,0]
	v_pk_mul_f32 v[52:53], v[128:129], v[136:137] op_sel_hi:[1,0]
	v_pk_mul_f32 v[42:43], v[54:55], v[42:43]
	v_pk_mul_f32 v[48:49], v[52:53], v[48:49]
	v_pk_mul_f32 v[52:53], v[124:125], v[136:137] op_sel_hi:[1,0]
	v_max_f32_e32 v46, 0, v46
	v_pk_mul_f32 v[44:45], v[52:53], v[44:45]
	v_max_f32_e32 v42, 0, v42
	v_max_f32_e32 v47, 0, v47
	v_max_f32_e32 v43, 0, v43
	v_pk_mul_f32 v[46:47], v[46:47], v[46:47]
	v_pk_mul_f32 v[52:53], v[42:43], v[42:43]
	v_max_f32_e32 v42, 0, v48
	v_max_f32_e32 v44, 0, v44
	v_max_f32_e32 v43, 0, v49
	v_max_f32_e32 v45, 0, v45
	v_cvt_f32_i32_e32 v39, v39
	v_cvt_f32_i32_e32 v38, v38
	v_pk_mul_f32 v[48:49], v[42:43], v[42:43]
	v_pk_mul_f32 v[54:55], v[44:45], v[44:45]
	v_cvt_pk_bf16_f32 v42, v46, v47
	v_add_co_u32_e32 v46, vcc, s54, v132
	v_cvt_f32_i32_e32 v41, v41
	v_cvt_f32_i32_e32 v40, v40
	v_cvt_f32_i32_e32 v35, v35
	v_cvt_f32_i32_e32 v34, v34
	v_cvt_pk_bf16_f32 v43, v48, v49
	v_cvt_pk_bf16_f32 v44, v52, v53
	v_cvt_pk_bf16_f32 v45, v54, v55
	v_addc_co_u32_e32 v47, vcc, 0, v133, vcc
	v_cvt_f32_i32_e32 v37, v37
	v_cvt_f32_i32_e32 v36, v36
	global_store_dwordx4 v[46:47], v[42:45], off nt
	v_cvt_f32_i32_e32 v31, v31
	v_cvt_f32_i32_e32 v30, v30
	v_pk_mul_f32 v[44:45], v[110:111], v[136:137] op_sel_hi:[1,0]
	v_pk_mul_f32 v[42:43], v[112:113], v[136:137] op_sel_hi:[1,0]
	v_pk_mul_f32 v[38:39], v[44:45], v[38:39]
	v_pk_mul_f32 v[44:45], v[106:107], v[136:137] op_sel_hi:[1,0]
	v_pk_mul_f32 v[40:41], v[42:43], v[40:41]
	v_pk_mul_f32 v[42:43], v[108:109], v[136:137] op_sel_hi:[1,0]
	v_pk_mul_f32 v[34:35], v[44:45], v[34:35]
	v_pk_mul_f32 v[36:37], v[42:43], v[36:37]
	v_max_f32_e32 v34, 0, v34
	v_max_f32_e32 v35, 0, v35
	v_max_f32_e32 v38, 0, v38
	v_max_f32_e32 v39, 0, v39
	v_pk_mul_f32 v[42:43], v[34:35], v[34:35]
	v_max_f32_e32 v34, 0, v40
	v_max_f32_e32 v36, 0, v36
	v_max_f32_e32 v35, 0, v41
	v_max_f32_e32 v37, 0, v37
	v_cvt_f32_i32_e32 v33, v33
	v_cvt_f32_i32_e32 v32, v32
	v_cvt_f32_i32_e32 v27, v27
	v_cvt_f32_i32_e32 v26, v26
	v_pk_mul_f32 v[38:39], v[38:39], v[38:39]
	v_pk_mul_f32 v[40:41], v[34:35], v[34:35]
	v_pk_mul_f32 v[44:45], v[36:37], v[36:37]
	v_cvt_f32_i32_e32 v29, v29
	v_cvt_f32_i32_e32 v28, v28
	v_lshl_add_u64 v[50:51], v[132:133], 0, s[12:13]
	v_cvt_pk_bf16_f32 v34, v38, v39
	v_cvt_pk_bf16_f32 v35, v40, v41
	v_cvt_pk_bf16_f32 v36, v42, v43
	v_cvt_pk_bf16_f32 v37, v44, v45
	v_pk_mul_f32 v[38:39], v[126:127], v[134:135] op_sel_hi:[1,0]
	global_store_dwordx4 v[50:51], v[34:37], off offset:256 nt
	v_pk_mul_f32 v[30:31], v[38:39], v[30:31]
	v_pk_mul_f32 v[38:39], v[122:123], v[134:135] op_sel_hi:[1,0]
	v_pk_mul_f32 v[36:37], v[128:129], v[134:135] op_sel_hi:[1,0]
	v_pk_mul_f32 v[26:27], v[38:39], v[26:27]
	v_pk_mul_f32 v[32:33], v[36:37], v[32:33]
	v_pk_mul_f32 v[36:37], v[124:125], v[134:135] op_sel_hi:[1,0]
	v_max_f32_e32 v30, 0, v30
	v_pk_mul_f32 v[28:29], v[36:37], v[28:29]
	v_max_f32_e32 v26, 0, v26
	v_max_f32_e32 v31, 0, v31
	v_max_f32_e32 v27, 0, v27
	v_pk_mul_f32 v[30:31], v[30:31], v[30:31]
	v_pk_mul_f32 v[36:37], v[26:27], v[26:27]
	v_max_f32_e32 v26, 0, v32
	v_max_f32_e32 v28, 0, v28
	v_max_f32_e32 v27, 0, v33
	v_max_f32_e32 v29, 0, v29
	v_cvt_f32_i32_e32 v23, v23
	v_cvt_f32_i32_e32 v22, v22
	v_pk_mul_f32 v[32:33], v[26:27], v[26:27]
	v_pk_mul_f32 v[38:39], v[28:29], v[28:29]
	v_cvt_pk_bf16_f32 v26, v30, v31
	v_add_co_u32_e32 v30, vcc, s55, v132
	v_cvt_f32_i32_e32 v25, v25
	v_cvt_f32_i32_e32 v24, v24
	v_cvt_f32_i32_e32 v19, v19
	v_cvt_f32_i32_e32 v18, v18
	v_cvt_pk_bf16_f32 v27, v32, v33
	v_cvt_pk_bf16_f32 v28, v36, v37
	v_cvt_pk_bf16_f32 v29, v38, v39
	v_addc_co_u32_e32 v31, vcc, 0, v133, vcc
	v_cvt_f32_i32_e32 v21, v21
	v_cvt_f32_i32_e32 v20, v20
	global_store_dwordx4 v[30:31], v[26:29], off nt
	v_cvt_f32_i32_e32 v15, v15
	v_cvt_f32_i32_e32 v14, v14
	v_pk_mul_f32 v[28:29], v[110:111], v[134:135] op_sel_hi:[1,0]
	v_pk_mul_f32 v[26:27], v[112:113], v[134:135] op_sel_hi:[1,0]
	v_pk_mul_f32 v[22:23], v[28:29], v[22:23]
	v_pk_mul_f32 v[28:29], v[106:107], v[134:135] op_sel_hi:[1,0]
	v_pk_mul_f32 v[24:25], v[26:27], v[24:25]
	v_pk_mul_f32 v[26:27], v[108:109], v[134:135] op_sel_hi:[1,0]
	v_pk_mul_f32 v[18:19], v[28:29], v[18:19]
	v_pk_mul_f32 v[20:21], v[26:27], v[20:21]
	v_max_f32_e32 v18, 0, v18
	v_max_f32_e32 v19, 0, v19
	v_max_f32_e32 v22, 0, v22
	v_max_f32_e32 v23, 0, v23
	v_pk_mul_f32 v[26:27], v[18:19], v[18:19]
	v_max_f32_e32 v18, 0, v24
	v_max_f32_e32 v20, 0, v20
	v_max_f32_e32 v19, 0, v25
	v_max_f32_e32 v21, 0, v21
	v_cvt_f32_i32_e32 v17, v17
	v_cvt_f32_i32_e32 v16, v16
	v_cvt_f32_i32_e32 v11, v11
	v_cvt_f32_i32_e32 v10, v10
	v_pk_mul_f32 v[22:23], v[22:23], v[22:23]
	v_pk_mul_f32 v[24:25], v[18:19], v[18:19]
	v_pk_mul_f32 v[28:29], v[20:21], v[20:21]
	v_cvt_f32_i32_e32 v13, v13
	v_cvt_f32_i32_e32 v12, v12
	v_lshl_add_u64 v[34:35], v[132:133], 0, s[14:15]
	v_cvt_pk_bf16_f32 v18, v22, v23
	v_cvt_pk_bf16_f32 v19, v24, v25
	v_cvt_pk_bf16_f32 v20, v26, v27
	v_cvt_pk_bf16_f32 v21, v28, v29
	v_pk_mul_f32 v[22:23], v[126:127], v[130:131] op_sel_hi:[1,0]
	global_store_dwordx4 v[34:35], v[18:21], off offset:256 nt
	v_pk_mul_f32 v[14:15], v[22:23], v[14:15]
	v_pk_mul_f32 v[22:23], v[122:123], v[130:131] op_sel_hi:[1,0]
	v_pk_mul_f32 v[20:21], v[128:129], v[130:131] op_sel_hi:[1,0]
	v_pk_mul_f32 v[10:11], v[22:23], v[10:11]
	v_pk_mul_f32 v[16:17], v[20:21], v[16:17]
	v_pk_mul_f32 v[20:21], v[124:125], v[130:131] op_sel_hi:[1,0]
	v_max_f32_e32 v14, 0, v14
	v_pk_mul_f32 v[12:13], v[20:21], v[12:13]
	v_max_f32_e32 v10, 0, v10
	v_max_f32_e32 v15, 0, v15
	v_max_f32_e32 v11, 0, v11
	v_pk_mul_f32 v[14:15], v[14:15], v[14:15]
	v_pk_mul_f32 v[20:21], v[10:11], v[10:11]
	v_max_f32_e32 v10, 0, v16
	v_max_f32_e32 v12, 0, v12
	v_max_f32_e32 v11, 0, v17
	v_max_f32_e32 v13, 0, v13
	v_cvt_f32_i32_e32 v7, v7
	v_cvt_f32_i32_e32 v6, v6
	v_pk_mul_f32 v[16:17], v[10:11], v[10:11]
	v_pk_mul_f32 v[22:23], v[12:13], v[12:13]
	v_cvt_pk_bf16_f32 v10, v14, v15
	v_add_co_u32_e32 v14, vcc, s56, v132
	v_cvt_f32_i32_e32 v9, v9
	v_cvt_f32_i32_e32 v8, v8
	v_cvt_f32_i32_e32 v3, v3
	v_cvt_f32_i32_e32 v2, v2
	v_cvt_pk_bf16_f32 v11, v16, v17
	v_cvt_pk_bf16_f32 v12, v20, v21
	v_cvt_pk_bf16_f32 v13, v22, v23
	v_addc_co_u32_e32 v15, vcc, 0, v133, vcc
	v_cvt_f32_i32_e32 v5, v5
	v_cvt_f32_i32_e32 v4, v4
	global_store_dwordx4 v[14:15], v[10:13], off nt
	v_lshl_add_u64 v[18:19], v[132:133], 0, s[16:17]
	s_andn2_b64 vcc, exec, s[2:3]
	v_pk_mul_f32 v[12:13], v[110:111], v[130:131] op_sel_hi:[1,0]
	v_pk_mul_f32 v[10:11], v[112:113], v[130:131] op_sel_hi:[1,0]
	v_pk_mul_f32 v[6:7], v[12:13], v[6:7]
	v_pk_mul_f32 v[12:13], v[106:107], v[130:131] op_sel_hi:[1,0]
	v_pk_mul_f32 v[8:9], v[10:11], v[8:9]
	v_pk_mul_f32 v[10:11], v[108:109], v[130:131] op_sel_hi:[1,0]
	v_pk_mul_f32 v[2:3], v[12:13], v[2:3]
	v_pk_mul_f32 v[4:5], v[10:11], v[4:5]
	v_max_f32_e32 v2, 0, v2
	v_max_f32_e32 v3, 0, v3
	v_max_f32_e32 v6, 0, v6
	v_max_f32_e32 v7, 0, v7
	v_pk_mul_f32 v[10:11], v[2:3], v[2:3]
	v_max_f32_e32 v2, 0, v8
	v_max_f32_e32 v4, 0, v4
	v_max_f32_e32 v3, 0, v9
	v_max_f32_e32 v5, 0, v5
	v_pk_mul_f32 v[6:7], v[6:7], v[6:7]
	v_pk_mul_f32 v[8:9], v[2:3], v[2:3]
	v_pk_mul_f32 v[12:13], v[4:5], v[4:5]
	v_cvt_pk_bf16_f32 v2, v6, v7
	v_cvt_pk_bf16_f32 v3, v8, v9
	v_cvt_pk_bf16_f32 v4, v10, v11
	v_cvt_pk_bf16_f32 v5, v12, v13
	s_mov_b64 s[2:3], -1
	global_store_dwordx4 v[18:19], v[2:5], off offset:256 nt
	s_cbranch_vccnz .LBB0_840
	s_andn2_b64 vcc, exec, s[0:1]
	s_cbranch_vccnz .LBB0_839
	s_barrier
	s_branch .LBB0_839

.LBB0_866:
	s_add_i32 s20, s20, 1
	s_mul_i32 s10, s20, s23
	s_mul_hi_u32 s11, s20, s96
	v_max_f32_e32 v122, v122, v122
	v_max_f32_e32 v123, v123, v123
	s_add_i32 s11, s11, s10
	s_mul_i32 s10, s20, s96
	v_mov_b64_e32 v[158:159], s[4:5]
	v_max_f32_e32 v122, 0, v122
	v_max_f32_e32 v123, 0, v123
	v_cmp_ge_i64_e32 vcc, s[10:11], v[158:159]
	v_pk_mul_f32 v[158:159], v[122:123], v[122:123]
	v_max_f32_e32 v123, v124, v124
	v_max_f32_e32 v126, v126, v126
	v_max_f32_e32 v127, v127, v127
	v_max_f32_e32 v122, v128, v128
	v_max_f32_e32 v124, 0, v123
	v_max_f32_e32 v123, v129, v129
	v_max_f32_e32 v125, v125, v125
	v_max_f32_e32 v126, 0, v126
	v_max_f32_e32 v127, 0, v127
	v_max_f32_e32 v122, 0, v122
	v_max_f32_e32 v123, 0, v123
	v_max_f32_e32 v125, 0, v125
	v_pk_mul_f32 v[126:127], v[126:127], v[126:127]
	v_pk_mul_f32 v[128:129], v[122:123], v[122:123]
	v_pk_mul_f32 v[160:161], v[124:125], v[124:125]
	v_max_f32_e32 v114, v114, v114
	v_max_f32_e32 v115, v115, v115
	v_cvt_pk_bf16_f32 v122, v126, v127
	v_cvt_pk_bf16_f32 v123, v128, v129
	v_cvt_pk_bf16_f32 v124, v158, v159
	v_cvt_pk_bf16_f32 v125, v160, v161
	v_max_f32_e32 v114, 0, v114
	v_max_f32_e32 v115, 0, v115
	global_store_dwordx4 v[134:135], v[122:125], off nt
	v_max_f32_e32 v118, v118, v118
	v_max_f32_e32 v119, v119, v119
	v_pk_mul_f32 v[122:123], v[114:115], v[114:115]
	v_max_f32_e32 v115, v116, v116
	v_max_f32_e32 v114, v120, v120
	v_max_f32_e32 v116, 0, v115
	v_max_f32_e32 v115, v121, v121
	v_max_f32_e32 v117, v117, v117
	v_max_f32_e32 v118, 0, v118
	v_max_f32_e32 v119, 0, v119
	v_max_f32_e32 v114, 0, v114
	v_max_f32_e32 v115, 0, v115
	v_max_f32_e32 v117, 0, v117
	v_pk_mul_f32 v[118:119], v[118:119], v[118:119]
	v_pk_mul_f32 v[120:121], v[114:115], v[114:115]
	v_pk_mul_f32 v[124:125], v[116:117], v[116:117]
	v_max_f32_e32 v106, v106, v106
	v_max_f32_e32 v107, v107, v107
	v_cvt_pk_bf16_f32 v114, v118, v119
	v_cvt_pk_bf16_f32 v115, v120, v121
	v_cvt_pk_bf16_f32 v116, v122, v123
	v_cvt_pk_bf16_f32 v117, v124, v125
	v_max_f32_e32 v106, 0, v106
	v_max_f32_e32 v107, 0, v107
	global_store_dwordx4 v[134:135], v[114:117], off offset:256 nt
	v_max_f32_e32 v110, v110, v110
	v_max_f32_e32 v111, v111, v111
	v_pk_mul_f32 v[114:115], v[106:107], v[106:107]
	v_max_f32_e32 v107, v108, v108
	v_max_f32_e32 v106, v112, v112
	v_max_f32_e32 v108, 0, v107
	v_max_f32_e32 v107, v113, v113
	v_max_f32_e32 v109, v109, v109
	v_max_f32_e32 v110, 0, v110
	v_max_f32_e32 v111, 0, v111
	v_max_f32_e32 v106, 0, v106
	v_max_f32_e32 v107, 0, v107
	v_max_f32_e32 v109, 0, v109
	v_pk_mul_f32 v[110:111], v[110:111], v[110:111]
	v_pk_mul_f32 v[112:113], v[106:107], v[106:107]
	v_pk_mul_f32 v[116:117], v[108:109], v[108:109]
	v_max_f32_e32 v98, v98, v98
	v_max_f32_e32 v99, v99, v99
	v_cvt_pk_bf16_f32 v106, v110, v111
	v_cvt_pk_bf16_f32 v107, v112, v113
	v_cvt_pk_bf16_f32 v108, v114, v115
	v_cvt_pk_bf16_f32 v109, v116, v117
	v_max_f32_e32 v98, 0, v98
	v_max_f32_e32 v99, 0, v99
	global_store_dwordx4 v[136:137], v[106:109], off nt
	v_max_f32_e32 v102, v102, v102
	v_max_f32_e32 v103, v103, v103
	v_pk_mul_f32 v[106:107], v[98:99], v[98:99]
	v_max_f32_e32 v99, v100, v100
	v_max_f32_e32 v98, v104, v104
	v_max_f32_e32 v100, 0, v99
	v_max_f32_e32 v99, v105, v105
	v_max_f32_e32 v101, v101, v101
	v_max_f32_e32 v102, 0, v102
	v_max_f32_e32 v103, 0, v103
	v_max_f32_e32 v98, 0, v98
	v_max_f32_e32 v99, 0, v99
	v_max_f32_e32 v101, 0, v101
	v_pk_mul_f32 v[102:103], v[102:103], v[102:103]
	v_pk_mul_f32 v[104:105], v[98:99], v[98:99]
	v_pk_mul_f32 v[108:109], v[100:101], v[100:101]
	v_max_f32_e32 v90, v90, v90
	v_max_f32_e32 v91, v91, v91
	v_cvt_pk_bf16_f32 v98, v102, v103
	v_cvt_pk_bf16_f32 v99, v104, v105
	v_cvt_pk_bf16_f32 v100, v106, v107
	v_cvt_pk_bf16_f32 v101, v108, v109
	v_max_f32_e32 v90, 0, v90
	v_max_f32_e32 v91, 0, v91
	global_store_dwordx4 v[136:137], v[98:101], off offset:256 nt
	v_max_f32_e32 v94, v94, v94
	v_max_f32_e32 v95, v95, v95
	v_pk_mul_f32 v[98:99], v[90:91], v[90:91]
	v_max_f32_e32 v91, v92, v92
	v_max_f32_e32 v90, v96, v96
	v_max_f32_e32 v92, 0, v91
	v_max_f32_e32 v91, v97, v97
	v_max_f32_e32 v93, v93, v93
	v_max_f32_e32 v94, 0, v94
	v_max_f32_e32 v95, 0, v95
	v_max_f32_e32 v90, 0, v90
	v_max_f32_e32 v91, 0, v91
	v_max_f32_e32 v93, 0, v93
	v_pk_mul_f32 v[94:95], v[94:95], v[94:95]
	v_pk_mul_f32 v[96:97], v[90:91], v[90:91]
	v_pk_mul_f32 v[100:101], v[92:93], v[92:93]
	v_max_f32_e32 v82, v82, v82
	v_max_f32_e32 v83, v83, v83
	v_cvt_pk_bf16_f32 v90, v94, v95
	v_cvt_pk_bf16_f32 v91, v96, v97
	v_cvt_pk_bf16_f32 v92, v98, v99
	v_cvt_pk_bf16_f32 v93, v100, v101
	v_max_f32_e32 v82, 0, v82
	v_max_f32_e32 v83, 0, v83
	global_store_dwordx4 v[138:139], v[90:93], off nt
	v_max_f32_e32 v86, v86, v86
	v_max_f32_e32 v87, v87, v87
	v_pk_mul_f32 v[90:91], v[82:83], v[82:83]
	v_max_f32_e32 v83, v84, v84
	v_max_f32_e32 v82, v88, v88
	v_max_f32_e32 v84, 0, v83
	v_max_f32_e32 v83, v89, v89
	v_max_f32_e32 v85, v85, v85
	v_max_f32_e32 v86, 0, v86
	v_max_f32_e32 v87, 0, v87
	v_max_f32_e32 v82, 0, v82
	v_max_f32_e32 v83, 0, v83
	v_max_f32_e32 v85, 0, v85
	v_pk_mul_f32 v[86:87], v[86:87], v[86:87]
	v_pk_mul_f32 v[88:89], v[82:83], v[82:83]
	v_pk_mul_f32 v[92:93], v[84:85], v[84:85]
	v_max_f32_e32 v74, v74, v74
	v_max_f32_e32 v75, v75, v75
	v_cvt_pk_bf16_f32 v82, v86, v87
	v_cvt_pk_bf16_f32 v83, v88, v89
	v_cvt_pk_bf16_f32 v84, v90, v91
	v_cvt_pk_bf16_f32 v85, v92, v93
	v_max_f32_e32 v74, 0, v74
	v_max_f32_e32 v75, 0, v75
	global_store_dwordx4 v[138:139], v[82:85], off offset:256 nt
	v_max_f32_e32 v78, v78, v78
	v_max_f32_e32 v79, v79, v79
	v_pk_mul_f32 v[82:83], v[74:75], v[74:75]
	v_max_f32_e32 v75, v76, v76
	v_max_f32_e32 v74, v80, v80
	v_max_f32_e32 v76, 0, v75
	v_max_f32_e32 v75, v81, v81
	v_max_f32_e32 v77, v77, v77
	v_max_f32_e32 v78, 0, v78
	v_max_f32_e32 v79, 0, v79
	v_max_f32_e32 v74, 0, v74
	v_max_f32_e32 v75, 0, v75
	v_max_f32_e32 v77, 0, v77
	v_pk_mul_f32 v[78:79], v[78:79], v[78:79]
	v_pk_mul_f32 v[80:81], v[74:75], v[74:75]
	v_pk_mul_f32 v[84:85], v[76:77], v[76:77]
	v_max_f32_e32 v66, v66, v66
	v_max_f32_e32 v67, v67, v67
	v_cvt_pk_bf16_f32 v74, v78, v79
	v_cvt_pk_bf16_f32 v75, v80, v81
	v_cvt_pk_bf16_f32 v76, v82, v83
	v_cvt_pk_bf16_f32 v77, v84, v85
	v_max_f32_e32 v66, 0, v66
	v_max_f32_e32 v67, 0, v67
	global_store_dwordx4 v[140:141], v[74:77], off nt
	v_max_f32_e32 v70, v70, v70
	v_max_f32_e32 v71, v71, v71
	v_pk_mul_f32 v[74:75], v[66:67], v[66:67]
	v_max_f32_e32 v67, v68, v68
	v_max_f32_e32 v66, v72, v72
	v_max_f32_e32 v68, 0, v67
	v_max_f32_e32 v67, v73, v73
	v_max_f32_e32 v69, v69, v69
	v_max_f32_e32 v70, 0, v70
	v_max_f32_e32 v71, 0, v71
	v_max_f32_e32 v66, 0, v66
	v_max_f32_e32 v67, 0, v67
	v_max_f32_e32 v69, 0, v69
	v_pk_mul_f32 v[70:71], v[70:71], v[70:71]
	v_pk_mul_f32 v[72:73], v[66:67], v[66:67]
	v_pk_mul_f32 v[76:77], v[68:69], v[68:69]
	v_max_f32_e32 v58, v58, v58
	v_max_f32_e32 v59, v59, v59
	v_cvt_pk_bf16_f32 v66, v70, v71
	v_cvt_pk_bf16_f32 v67, v72, v73
	v_cvt_pk_bf16_f32 v68, v74, v75
	v_cvt_pk_bf16_f32 v69, v76, v77
	v_max_f32_e32 v58, 0, v58
	v_max_f32_e32 v59, 0, v59
	global_store_dwordx4 v[140:141], v[66:69], off offset:256 nt
	v_max_f32_e32 v62, v62, v62
	v_max_f32_e32 v63, v63, v63
	v_pk_mul_f32 v[66:67], v[58:59], v[58:59]
	v_max_f32_e32 v59, v60, v60
	v_max_f32_e32 v58, v64, v64
	v_max_f32_e32 v60, 0, v59
	v_max_f32_e32 v59, v65, v65
	v_max_f32_e32 v61, v61, v61
	v_max_f32_e32 v62, 0, v62
	v_max_f32_e32 v63, 0, v63
	v_max_f32_e32 v58, 0, v58
	v_max_f32_e32 v59, 0, v59
	v_max_f32_e32 v61, 0, v61
	v_pk_mul_f32 v[62:63], v[62:63], v[62:63]
	v_pk_mul_f32 v[64:65], v[58:59], v[58:59]
	v_pk_mul_f32 v[68:69], v[60:61], v[60:61]
	v_max_f32_e32 v50, v50, v50
	v_max_f32_e32 v51, v51, v51
	v_cvt_pk_bf16_f32 v58, v62, v63
	v_cvt_pk_bf16_f32 v59, v64, v65
	v_cvt_pk_bf16_f32 v60, v66, v67
	v_cvt_pk_bf16_f32 v61, v68, v69
	v_max_f32_e32 v50, 0, v50
	v_max_f32_e32 v51, 0, v51
	global_store_dwordx4 v[142:143], v[58:61], off nt
	v_max_f32_e32 v54, v54, v54
	v_max_f32_e32 v55, v55, v55
	v_pk_mul_f32 v[58:59], v[50:51], v[50:51]
	v_max_f32_e32 v51, v52, v52
	v_max_f32_e32 v50, v56, v56
	v_max_f32_e32 v52, 0, v51
	v_max_f32_e32 v51, v57, v57
	v_max_f32_e32 v53, v53, v53
	v_max_f32_e32 v54, 0, v54
	v_max_f32_e32 v55, 0, v55
	v_max_f32_e32 v50, 0, v50
	v_max_f32_e32 v51, 0, v51
	v_max_f32_e32 v53, 0, v53
	v_pk_mul_f32 v[54:55], v[54:55], v[54:55]
	v_pk_mul_f32 v[56:57], v[50:51], v[50:51]
	v_pk_mul_f32 v[60:61], v[52:53], v[52:53]
	v_max_f32_e32 v42, v42, v42
	v_max_f32_e32 v43, v43, v43
	v_cvt_pk_bf16_f32 v50, v54, v55
	v_cvt_pk_bf16_f32 v51, v56, v57
	v_cvt_pk_bf16_f32 v52, v58, v59
	v_cvt_pk_bf16_f32 v53, v60, v61
	v_max_f32_e32 v42, 0, v42
	v_max_f32_e32 v43, 0, v43
	global_store_dwordx4 v[142:143], v[50:53], off offset:256 nt
	v_max_f32_e32 v46, v46, v46
	v_max_f32_e32 v47, v47, v47
	v_pk_mul_f32 v[50:51], v[42:43], v[42:43]
	v_max_f32_e32 v43, v44, v44
	v_max_f32_e32 v42, v48, v48
	v_max_f32_e32 v44, 0, v43
	v_max_f32_e32 v43, v49, v49
	v_max_f32_e32 v45, v45, v45
	v_max_f32_e32 v46, 0, v46
	v_max_f32_e32 v47, 0, v47
	v_max_f32_e32 v42, 0, v42
	v_max_f32_e32 v43, 0, v43
	v_max_f32_e32 v45, 0, v45
	v_pk_mul_f32 v[46:47], v[46:47], v[46:47]
	v_pk_mul_f32 v[48:49], v[42:43], v[42:43]
	v_pk_mul_f32 v[52:53], v[44:45], v[44:45]
	v_max_f32_e32 v34, v34, v34
	v_max_f32_e32 v35, v35, v35
	v_cvt_pk_bf16_f32 v42, v46, v47
	v_cvt_pk_bf16_f32 v43, v48, v49
	v_cvt_pk_bf16_f32 v44, v50, v51
	v_cvt_pk_bf16_f32 v45, v52, v53
	v_max_f32_e32 v34, 0, v34
	v_max_f32_e32 v35, 0, v35
	global_store_dwordx4 v[144:145], v[42:45], off nt
	v_max_f32_e32 v38, v38, v38
	v_max_f32_e32 v39, v39, v39
	v_pk_mul_f32 v[42:43], v[34:35], v[34:35]
	v_max_f32_e32 v35, v36, v36
	v_max_f32_e32 v34, v40, v40
	v_max_f32_e32 v36, 0, v35
	v_max_f32_e32 v35, v41, v41
	v_max_f32_e32 v37, v37, v37
	v_max_f32_e32 v38, 0, v38
	v_max_f32_e32 v39, 0, v39
	v_max_f32_e32 v34, 0, v34
	v_max_f32_e32 v35, 0, v35
	v_max_f32_e32 v37, 0, v37
	v_pk_mul_f32 v[38:39], v[38:39], v[38:39]
	v_pk_mul_f32 v[40:41], v[34:35], v[34:35]
	v_pk_mul_f32 v[44:45], v[36:37], v[36:37]
	v_max_f32_e32 v26, v26, v26
	v_max_f32_e32 v27, v27, v27
	v_cvt_pk_bf16_f32 v34, v38, v39
	v_cvt_pk_bf16_f32 v35, v40, v41
	v_cvt_pk_bf16_f32 v36, v42, v43
	v_cvt_pk_bf16_f32 v37, v44, v45
	v_max_f32_e32 v26, 0, v26
	v_max_f32_e32 v27, 0, v27
	global_store_dwordx4 v[144:145], v[34:37], off offset:256 nt
	v_max_f32_e32 v30, v30, v30
	v_max_f32_e32 v31, v31, v31
	v_pk_mul_f32 v[34:35], v[26:27], v[26:27]
	v_max_f32_e32 v27, v28, v28
	v_max_f32_e32 v26, v32, v32
	v_max_f32_e32 v28, 0, v27
	v_max_f32_e32 v27, v33, v33
	v_max_f32_e32 v29, v29, v29
	v_max_f32_e32 v30, 0, v30
	v_max_f32_e32 v31, 0, v31
	v_max_f32_e32 v26, 0, v26
	v_max_f32_e32 v27, 0, v27
	v_max_f32_e32 v29, 0, v29
	v_pk_mul_f32 v[30:31], v[30:31], v[30:31]
	v_pk_mul_f32 v[32:33], v[26:27], v[26:27]
	v_pk_mul_f32 v[36:37], v[28:29], v[28:29]
	v_max_f32_e32 v18, v18, v18
	v_max_f32_e32 v19, v19, v19
	v_cvt_pk_bf16_f32 v26, v30, v31
	v_cvt_pk_bf16_f32 v27, v32, v33
	v_cvt_pk_bf16_f32 v28, v34, v35
	v_cvt_pk_bf16_f32 v29, v36, v37
	v_max_f32_e32 v18, 0, v18
	v_max_f32_e32 v19, 0, v19
	global_store_dwordx4 v[146:147], v[26:29], off nt
	v_max_f32_e32 v22, v22, v22
	v_max_f32_e32 v23, v23, v23
	v_pk_mul_f32 v[26:27], v[18:19], v[18:19]
	v_max_f32_e32 v19, v20, v20
	v_max_f32_e32 v18, v24, v24
	v_max_f32_e32 v20, 0, v19
	v_max_f32_e32 v19, v25, v25
	v_max_f32_e32 v21, v21, v21
	v_max_f32_e32 v22, 0, v22
	v_max_f32_e32 v23, 0, v23
	v_max_f32_e32 v18, 0, v18
	v_max_f32_e32 v19, 0, v19
	v_max_f32_e32 v21, 0, v21
	v_pk_mul_f32 v[22:23], v[22:23], v[22:23]
	v_pk_mul_f32 v[24:25], v[18:19], v[18:19]
	v_pk_mul_f32 v[28:29], v[20:21], v[20:21]
	v_max_f32_e32 v10, v10, v10
	v_max_f32_e32 v11, v11, v11
	v_cvt_pk_bf16_f32 v18, v22, v23
	v_cvt_pk_bf16_f32 v19, v24, v25
	v_cvt_pk_bf16_f32 v20, v26, v27
	v_cvt_pk_bf16_f32 v21, v28, v29
	v_max_f32_e32 v10, 0, v10
	v_max_f32_e32 v11, 0, v11
	global_store_dwordx4 v[146:147], v[18:21], off offset:256 nt
	v_max_f32_e32 v14, v14, v14
	v_max_f32_e32 v15, v15, v15
	v_pk_mul_f32 v[18:19], v[10:11], v[10:11]
	v_max_f32_e32 v11, v12, v12
	v_max_f32_e32 v10, v16, v16
	v_max_f32_e32 v12, 0, v11
	v_max_f32_e32 v11, v17, v17
	v_max_f32_e32 v13, v13, v13
	v_max_f32_e32 v14, 0, v14
	v_max_f32_e32 v15, 0, v15
	v_max_f32_e32 v10, 0, v10
	v_max_f32_e32 v11, 0, v11
	v_max_f32_e32 v13, 0, v13
	v_pk_mul_f32 v[14:15], v[14:15], v[14:15]
	v_pk_mul_f32 v[16:17], v[10:11], v[10:11]
	v_pk_mul_f32 v[20:21], v[12:13], v[12:13]
	v_max_f32_e32 v2, v2, v2
	v_max_f32_e32 v3, v3, v3
	v_cvt_pk_bf16_f32 v10, v14, v15
	v_cvt_pk_bf16_f32 v11, v16, v17
	v_cvt_pk_bf16_f32 v12, v18, v19
	v_cvt_pk_bf16_f32 v13, v20, v21
	v_max_f32_e32 v2, 0, v2
	v_max_f32_e32 v3, 0, v3
	global_store_dwordx4 v[148:149], v[10:13], off nt
	v_max_f32_e32 v6, v6, v6
	v_max_f32_e32 v7, v7, v7
	v_pk_mul_f32 v[10:11], v[2:3], v[2:3]
	v_max_f32_e32 v3, v4, v4
	v_max_f32_e32 v2, v8, v8
	v_max_f32_e32 v4, 0, v3
	v_max_f32_e32 v3, v9, v9
	v_max_f32_e32 v5, v5, v5
	v_max_f32_e32 v6, 0, v6
	v_max_f32_e32 v7, 0, v7
	v_max_f32_e32 v2, 0, v2
	v_max_f32_e32 v3, 0, v3
	v_max_f32_e32 v5, 0, v5
	v_pk_mul_f32 v[6:7], v[6:7], v[6:7]
	v_pk_mul_f32 v[8:9], v[2:3], v[2:3]
	v_pk_mul_f32 v[12:13], v[4:5], v[4:5]
	v_cvt_pk_bf16_f32 v2, v6, v7
	v_cvt_pk_bf16_f32 v3, v8, v9
	v_cvt_pk_bf16_f32 v4, v10, v11
	v_cvt_pk_bf16_f32 v5, v12, v13
	s_mov_b64 s[10:11], -1
	global_store_dwordx4 v[148:149], v[2:5], off offset:256 nt
	s_cbranch_vccnz .LBB0_861
	s_andn2_b64 vcc, exec, s[0:1]
	s_cbranch_vccnz .LBB0_860
	s_barrier
	s_branch .LBB0_860
